# speedup vs baseline: 1.0013x; 1.0013x over previous
.LBB0_119:
	s_ashr_i32 s5, s4, 31
	s_lshl_b64 s[0:1], s[4:5], 19
	v_lshl_add_u64 v[24:25], v[20:21], 0, s[0:1]
	s_lshl_b64 s[0:1], s[4:5], 18
	v_lshl_add_u64 v[26:27], v[22:23], 0, s[0:1]
	s_ashr_i32 s0, s4, 5
	s_mul_hi_i32 s1, s0, 0x6000
	s_mulk_i32 s0, 0x6000
	s_add_u32 s0, s8, s0
	s_addc_u32 s1, s9, s1
	s_add_u32 s6, s0, 0x1000
	s_addc_u32 s7, s1, 0
	global_load_dwordx4 v[28:31], v[18:19], off
	global_load_dwordx4 v[114:117], v0, s[6:7]
	global_load_dwordx4 v[2:5], v0, s[0:1]
	global_load_dwordx4 v[32:35], v[18:19], off offset:1024
	global_load_dwordx4 v[118:121], v50, s[6:7]
	global_load_dwordx4 v[6:9], v0, s[0:1] offset:1024
	global_load_dwordx4 v[36:39], v[18:19], off offset:2048
	global_load_dwordx4 v[122:125], v51, s[6:7]
	global_load_dwordx4 v[10:13], v0, s[0:1] offset:2048
	global_load_dwordx4 v[40:43], v[18:19], off offset:3072
	global_load_dwordx4 v[126:129], v52, s[6:7]
	global_load_dwordx4 v[14:17], v0, s[0:1] offset:3072
	global_load_dwordx4 v[54:57], v[24:25], off offset:-2048
	global_load_dwordx4 v[58:61], v[24:25], off offset:-1024
	global_load_dwordx4 v[62:65], v[24:25], off
	global_load_dwordx4 v[66:69], v[24:25], off offset:1024
	v_lshl_add_u64 v[24:25], v[24:25], 0, s[48:49]
	global_load_dwordx4 v[82:85], v[24:25], off offset:-2048
	global_load_dwordx4 v[86:89], v[24:25], off offset:-1024
	global_load_dwordx4 v[90:93], v[24:25], off
	global_load_dwordx4 v[94:97], v[24:25], off offset:1024
	v_lshl_add_u64 v[24:25], v[24:25], 0, s[48:49]
	global_load_dwordx4 v[98:101], v[24:25], off offset:-2048
	global_load_dwordx4 v[102:105], v[24:25], off offset:-1024
	global_load_dwordx4 v[106:109], v[24:25], off
	global_load_dwordx4 v[110:113], v[24:25], off offset:1024
	s_mov_b64 s[6:7], 0
	s_waitcnt vmcnt(12)
	v_pk_add_f32 v[114:115], v[114:115], 1.0 op_sel_hi:[1,0]
	v_pk_add_f32 v[116:117], v[116:117], 1.0 op_sel_hi:[1,0]
	v_pk_add_f32 v[118:119], v[118:119], 1.0 op_sel_hi:[1,0]
	v_pk_add_f32 v[120:121], v[120:121], 1.0 op_sel_hi:[1,0]
	v_pk_add_f32 v[122:123], v[122:123], 1.0 op_sel_hi:[1,0]
	v_pk_add_f32 v[124:125], v[124:125], 1.0 op_sel_hi:[1,0]
	v_pk_add_f32 v[126:127], v[126:127], 1.0 op_sel_hi:[1,0]
	v_pk_add_f32 v[128:129], v[128:129], 1.0 op_sel_hi:[1,0]
	v_pk_mul_f32 v[28:29], v[28:29], v[114:115]
	v_pk_mul_f32 v[30:31], v[30:31], v[116:117]
	v_pk_mul_f32 v[32:33], v[32:33], v[118:119]
	v_pk_mul_f32 v[34:35], v[34:35], v[120:121]
	v_pk_mul_f32 v[36:37], v[36:37], v[122:123]
	v_pk_mul_f32 v[38:39], v[38:39], v[124:125]
	v_pk_mul_f32 v[40:41], v[40:41], v[126:127]
	v_pk_mul_f32 v[42:43], v[42:43], v[128:129]
	v_lshl_add_u64 v[24:25], v[24:25], 0, s[48:49]
	global_load_dwordx4 v[114:117], v[24:25], off offset:-2048
	global_load_dwordx4 v[118:121], v[24:25], off offset:-1024
	global_load_dwordx4 v[122:125], v[24:25], off
	global_load_dwordx4 v[126:129], v[24:25], off offset:1024
	v_lshl_add_u64 v[70:71], v[26:27], 0, s[6:7]
	s_waitcnt vmcnt(12)
	v_mov_b32_e32 v80, v55
	v_mov_b32_e32 v81, v59
	v_mov_b32_e32 v78, v54
	v_mov_b32_e32 v79, v58
	v_pk_mul_f32 v[80:81], v[80:81], v[80:81]
	v_mov_b32_e32 v74, v56
	v_mov_b32_e32 v75, v60
	v_pk_fma_f32 v[78:79], v[78:79], v[78:79], v[80:81]
	v_mov_b32_e32 v76, v57
	v_mov_b32_e32 v77, v61
	v_pk_fma_f32 v[74:75], v[74:75], v[74:75], v[78:79]
	s_nop 0
	v_pk_fma_f32 v[72:73], v[76:77], v[76:77], v[74:75]
	s_nop 0
	v_add_f32_e32 v53, v72, v73
	v_mov_b32_e32 v80, v63
	v_mov_b32_e32 v81, v67
	v_mov_b32_e32 v78, v62
	v_mov_b32_e32 v79, v66
	v_pk_mul_f32 v[80:81], v[80:81], v[80:81]
	v_mov_b32_e32 v74, v64
	v_mov_b32_e32 v75, v68
	v_pk_fma_f32 v[78:79], v[78:79], v[78:79], v[80:81]
	v_mov_b32_e32 v76, v65
	v_mov_b32_e32 v77, v69
	v_pk_fma_f32 v[74:75], v[74:75], v[74:75], v[78:79]
	s_nop 0
	v_pk_fma_f32 v[74:75], v[76:77], v[76:77], v[74:75]
	s_nop 0
	v_add_f32_e32 v53, v53, v74
	v_add_f32_e32 v53, v53, v75
	ds_bpermute_b32 v72, v44, v53
	s_waitcnt lgkmcnt(0)
	v_add_f32_e32 v53, v53, v72
	ds_bpermute_b32 v72, v45, v53
	s_waitcnt lgkmcnt(0)
	v_add_f32_e32 v53, v53, v72
	ds_bpermute_b32 v72, v46, v53
	s_waitcnt lgkmcnt(0)
	v_add_f32_e32 v53, v53, v72
	ds_bpermute_b32 v72, v47, v53
	s_waitcnt lgkmcnt(0)
	v_add_f32_e32 v53, v53, v72
	ds_bpermute_b32 v72, v48, v53
	s_waitcnt lgkmcnt(0)
	v_add_f32_e32 v53, v53, v72
	ds_bpermute_b32 v72, v49, v53
	s_waitcnt lgkmcnt(0)
	v_add_f32_e32 v53, v53, v72
	v_fmamk_f32 v53, v53, 0x3a800000, v149
	v_cmp_gt_f32_e32 vcc, s26, v53
	v_mul_f32_e32 v72, 0x4b800000, v53
	s_nop 0
	v_cndmask_b32_e32 v53, v53, v72, vcc
	v_rsq_f32_e32 v53, v53
	s_nop 0
	v_mul_f32_e32 v72, 0x45800000, v53
	v_cndmask_b32_e32 v72, v53, v72, vcc
	v_pk_mul_f32 v[54:55], v[72:73], v[54:55] op_sel_hi:[0,1]
	v_pk_mul_f32 v[56:57], v[72:73], v[56:57] op_sel_hi:[0,1]
	v_pk_fma_f32 v[54:55], v[54:55], v[28:29], v[2:3]
	v_pk_fma_f32 v[56:57], v[56:57], v[30:31], v[4:5]
	v_cvt_pk_bf16_f32 v54, v54, v55
	v_cvt_pk_bf16_f32 v55, v56, v57
	global_store_dwordx2 v[70:71], v[54:55], off offset:-1024
	v_pk_mul_f32 v[54:55], v[72:73], v[58:59] op_sel_hi:[0,1]
	v_pk_mul_f32 v[56:57], v[72:73], v[60:61] op_sel_hi:[0,1]
	v_pk_fma_f32 v[54:55], v[54:55], v[32:33], v[6:7]
	v_pk_fma_f32 v[56:57], v[56:57], v[34:35], v[8:9]
	v_cvt_pk_bf16_f32 v54, v54, v55
	v_cvt_pk_bf16_f32 v55, v56, v57
	global_store_dwordx2 v[70:71], v[54:55], off offset:-512
	v_pk_mul_f32 v[54:55], v[72:73], v[62:63] op_sel_hi:[0,1]
	v_pk_mul_f32 v[56:57], v[72:73], v[64:65] op_sel_hi:[0,1]
	v_pk_fma_f32 v[54:55], v[54:55], v[36:37], v[10:11]
	v_pk_fma_f32 v[56:57], v[56:57], v[38:39], v[12:13]
	v_cvt_pk_bf16_f32 v54, v54, v55
	v_cvt_pk_bf16_f32 v55, v56, v57
	global_store_dwordx2 v[70:71], v[54:55], off
	v_pk_mul_f32 v[54:55], v[72:73], v[66:67] op_sel_hi:[0,1]
	v_pk_mul_f32 v[56:57], v[72:73], v[68:69] op_sel_hi:[0,1]
	v_pk_fma_f32 v[54:55], v[54:55], v[40:41], v[14:15]
	v_pk_fma_f32 v[56:57], v[56:57], v[42:43], v[16:17]
	v_cvt_pk_bf16_f32 v54, v54, v55
	v_cvt_pk_bf16_f32 v55, v56, v57
	global_store_dwordx2 v[70:71], v[54:55], off offset:512
	s_add_u32 s6, s6, 0x800
	s_addc_u32 s7, s7, 0
	v_lshl_add_u64 v[24:25], v[24:25], 0, s[48:49]
	global_load_dwordx4 v[54:57], v[24:25], off offset:-2048
	global_load_dwordx4 v[58:61], v[24:25], off offset:-1024
	global_load_dwordx4 v[62:65], v[24:25], off
	global_load_dwordx4 v[66:69], v[24:25], off offset:1024
	v_lshl_add_u64 v[70:71], v[26:27], 0, s[6:7]
	s_waitcnt vmcnt(16)
	v_mov_b32_e32 v80, v83
	v_mov_b32_e32 v81, v87
	v_mov_b32_e32 v78, v82
	v_mov_b32_e32 v79, v86
	v_pk_mul_f32 v[80:81], v[80:81], v[80:81]
	v_mov_b32_e32 v74, v84
	v_mov_b32_e32 v75, v88
	v_pk_fma_f32 v[78:79], v[78:79], v[78:79], v[80:81]
	v_mov_b32_e32 v76, v85
	v_mov_b32_e32 v77, v89
	v_pk_fma_f32 v[74:75], v[74:75], v[74:75], v[78:79]
	s_nop 0
	v_pk_fma_f32 v[72:73], v[76:77], v[76:77], v[74:75]
	s_nop 0
	v_add_f32_e32 v53, v72, v73
	v_mov_b32_e32 v80, v91
	v_mov_b32_e32 v81, v95
	v_mov_b32_e32 v78, v90
	v_mov_b32_e32 v79, v94
	v_pk_mul_f32 v[80:81], v[80:81], v[80:81]
	v_mov_b32_e32 v74, v92
	v_mov_b32_e32 v75, v96
	v_pk_fma_f32 v[78:79], v[78:79], v[78:79], v[80:81]
	v_mov_b32_e32 v76, v93
	v_mov_b32_e32 v77, v97
	v_pk_fma_f32 v[74:75], v[74:75], v[74:75], v[78:79]
	s_nop 0
	v_pk_fma_f32 v[74:75], v[76:77], v[76:77], v[74:75]
	s_nop 0
	v_add_f32_e32 v53, v53, v74
	v_add_f32_e32 v53, v53, v75
	ds_bpermute_b32 v72, v44, v53
	s_waitcnt lgkmcnt(0)
	v_add_f32_e32 v53, v53, v72
	ds_bpermute_b32 v72, v45, v53
	s_waitcnt lgkmcnt(0)
	v_add_f32_e32 v53, v53, v72
	ds_bpermute_b32 v72, v46, v53
	s_waitcnt lgkmcnt(0)
	v_add_f32_e32 v53, v53, v72
	ds_bpermute_b32 v72, v47, v53
	s_waitcnt lgkmcnt(0)
	v_add_f32_e32 v53, v53, v72
	ds_bpermute_b32 v72, v48, v53
	s_waitcnt lgkmcnt(0)
	v_add_f32_e32 v53, v53, v72
	ds_bpermute_b32 v72, v49, v53
	s_waitcnt lgkmcnt(0)
	v_add_f32_e32 v53, v53, v72
	v_fmamk_f32 v53, v53, 0x3a800000, v149
	v_cmp_gt_f32_e32 vcc, s26, v53
	v_mul_f32_e32 v72, 0x4b800000, v53
	s_nop 0
	v_cndmask_b32_e32 v53, v53, v72, vcc
	v_rsq_f32_e32 v53, v53
	s_nop 0
	v_mul_f32_e32 v72, 0x45800000, v53
	v_cndmask_b32_e32 v72, v53, v72, vcc
	v_pk_mul_f32 v[82:83], v[72:73], v[82:83] op_sel_hi:[0,1]
	v_pk_mul_f32 v[84:85], v[72:73], v[84:85] op_sel_hi:[0,1]
	v_pk_fma_f32 v[82:83], v[82:83], v[28:29], v[2:3]
	v_pk_fma_f32 v[84:85], v[84:85], v[30:31], v[4:5]
	v_cvt_pk_bf16_f32 v82, v82, v83
	v_cvt_pk_bf16_f32 v83, v84, v85
	global_store_dwordx2 v[70:71], v[82:83], off offset:-1024
	v_pk_mul_f32 v[82:83], v[72:73], v[86:87] op_sel_hi:[0,1]
	v_pk_mul_f32 v[84:85], v[72:73], v[88:89] op_sel_hi:[0,1]
	v_pk_fma_f32 v[82:83], v[82:83], v[32:33], v[6:7]
	v_pk_fma_f32 v[84:85], v[84:85], v[34:35], v[8:9]
	v_cvt_pk_bf16_f32 v82, v82, v83
	v_cvt_pk_bf16_f32 v83, v84, v85
	global_store_dwordx2 v[70:71], v[82:83], off offset:-512
	v_pk_mul_f32 v[82:83], v[72:73], v[90:91] op_sel_hi:[0,1]
	v_pk_mul_f32 v[84:85], v[72:73], v[92:93] op_sel_hi:[0,1]
	v_pk_fma_f32 v[82:83], v[82:83], v[36:37], v[10:11]
	v_pk_fma_f32 v[84:85], v[84:85], v[38:39], v[12:13]
	v_cvt_pk_bf16_f32 v82, v82, v83
	v_cvt_pk_bf16_f32 v83, v84, v85
	global_store_dwordx2 v[70:71], v[82:83], off
	v_pk_mul_f32 v[82:83], v[72:73], v[94:95] op_sel_hi:[0,1]
	v_pk_mul_f32 v[84:85], v[72:73], v[96:97] op_sel_hi:[0,1]
	v_pk_fma_f32 v[82:83], v[82:83], v[40:41], v[14:15]
	v_pk_fma_f32 v[84:85], v[84:85], v[42:43], v[16:17]
	v_cvt_pk_bf16_f32 v82, v82, v83
	v_cvt_pk_bf16_f32 v83, v84, v85
	global_store_dwordx2 v[70:71], v[82:83], off offset:512
	s_add_u32 s6, s6, 0x800
	s_addc_u32 s7, s7, 0
	v_lshl_add_u64 v[24:25], v[24:25], 0, s[48:49]
	global_load_dwordx4 v[82:85], v[24:25], off offset:-2048
	global_load_dwordx4 v[86:89], v[24:25], off offset:-1024
	global_load_dwordx4 v[90:93], v[24:25], off
	global_load_dwordx4 v[94:97], v[24:25], off offset:1024
	v_lshl_add_u64 v[70:71], v[26:27], 0, s[6:7]
	s_waitcnt vmcnt(20)
	v_mov_b32_e32 v80, v99
	v_mov_b32_e32 v81, v103
	v_mov_b32_e32 v78, v98
	v_mov_b32_e32 v79, v102
	v_pk_mul_f32 v[80:81], v[80:81], v[80:81]
	v_mov_b32_e32 v74, v100
	v_mov_b32_e32 v75, v104
	v_pk_fma_f32 v[78:79], v[78:79], v[78:79], v[80:81]
	v_mov_b32_e32 v76, v101
	v_mov_b32_e32 v77, v105
	v_pk_fma_f32 v[74:75], v[74:75], v[74:75], v[78:79]
	s_nop 0
	v_pk_fma_f32 v[72:73], v[76:77], v[76:77], v[74:75]
	s_nop 0
	v_add_f32_e32 v53, v72, v73
	v_mov_b32_e32 v80, v107
	v_mov_b32_e32 v81, v111
	v_mov_b32_e32 v78, v106
	v_mov_b32_e32 v79, v110
	v_pk_mul_f32 v[80:81], v[80:81], v[80:81]
	v_mov_b32_e32 v74, v108
	v_mov_b32_e32 v75, v112
	v_pk_fma_f32 v[78:79], v[78:79], v[78:79], v[80:81]
	v_mov_b32_e32 v76, v109
	v_mov_b32_e32 v77, v113
	v_pk_fma_f32 v[74:75], v[74:75], v[74:75], v[78:79]
	s_nop 0
	v_pk_fma_f32 v[74:75], v[76:77], v[76:77], v[74:75]
	s_nop 0
	v_add_f32_e32 v53, v53, v74
	v_add_f32_e32 v53, v53, v75
	ds_bpermute_b32 v72, v44, v53
	s_waitcnt lgkmcnt(0)
	v_add_f32_e32 v53, v53, v72
	ds_bpermute_b32 v72, v45, v53
	s_waitcnt lgkmcnt(0)
	v_add_f32_e32 v53, v53, v72
	ds_bpermute_b32 v72, v46, v53
	s_waitcnt lgkmcnt(0)
	v_add_f32_e32 v53, v53, v72
	ds_bpermute_b32 v72, v47, v53
	s_waitcnt lgkmcnt(0)
	v_add_f32_e32 v53, v53, v72
	ds_bpermute_b32 v72, v48, v53
	s_waitcnt lgkmcnt(0)
	v_add_f32_e32 v53, v53, v72
	ds_bpermute_b32 v72, v49, v53
	s_waitcnt lgkmcnt(0)
	v_add_f32_e32 v53, v53, v72
	v_fmamk_f32 v53, v53, 0x3a800000, v149
	v_cmp_gt_f32_e32 vcc, s26, v53
	v_mul_f32_e32 v72, 0x4b800000, v53
	s_nop 0
	v_cndmask_b32_e32 v53, v53, v72, vcc
	v_rsq_f32_e32 v53, v53
	s_nop 0
	v_mul_f32_e32 v72, 0x45800000, v53
	v_cndmask_b32_e32 v72, v53, v72, vcc
	v_pk_mul_f32 v[98:99], v[72:73], v[98:99] op_sel_hi:[0,1]
	v_pk_mul_f32 v[100:101], v[72:73], v[100:101] op_sel_hi:[0,1]
	v_pk_fma_f32 v[98:99], v[98:99], v[28:29], v[2:3]
	v_pk_fma_f32 v[100:101], v[100:101], v[30:31], v[4:5]
	v_cvt_pk_bf16_f32 v98, v98, v99
	v_cvt_pk_bf16_f32 v99, v100, v101
	global_store_dwordx2 v[70:71], v[98:99], off offset:-1024
	v_pk_mul_f32 v[98:99], v[72:73], v[102:103] op_sel_hi:[0,1]
	v_pk_mul_f32 v[100:101], v[72:73], v[104:105] op_sel_hi:[0,1]
	v_pk_fma_f32 v[98:99], v[98:99], v[32:33], v[6:7]
	v_pk_fma_f32 v[100:101], v[100:101], v[34:35], v[8:9]
	v_cvt_pk_bf16_f32 v98, v98, v99
	v_cvt_pk_bf16_f32 v99, v100, v101
	global_store_dwordx2 v[70:71], v[98:99], off offset:-512
	v_pk_mul_f32 v[98:99], v[72:73], v[106:107] op_sel_hi:[0,1]
	v_pk_mul_f32 v[100:101], v[72:73], v[108:109] op_sel_hi:[0,1]
	v_pk_fma_f32 v[98:99], v[98:99], v[36:37], v[10:11]
	v_pk_fma_f32 v[100:101], v[100:101], v[38:39], v[12:13]
	v_cvt_pk_bf16_f32 v98, v98, v99
	v_cvt_pk_bf16_f32 v99, v100, v101
	global_store_dwordx2 v[70:71], v[98:99], off
	v_pk_mul_f32 v[98:99], v[72:73], v[110:111] op_sel_hi:[0,1]
	v_pk_mul_f32 v[100:101], v[72:73], v[112:113] op_sel_hi:[0,1]
	v_pk_fma_f32 v[98:99], v[98:99], v[40:41], v[14:15]
	v_pk_fma_f32 v[100:101], v[100:101], v[42:43], v[16:17]
	v_cvt_pk_bf16_f32 v98, v98, v99
	v_cvt_pk_bf16_f32 v99, v100, v101
	global_store_dwordx2 v[70:71], v[98:99], off offset:512
	s_add_u32 s6, s6, 0x800
	s_addc_u32 s7, s7, 0
	v_lshl_add_u64 v[24:25], v[24:25], 0, s[48:49]
	global_load_dwordx4 v[98:101], v[24:25], off offset:-2048
	global_load_dwordx4 v[102:105], v[24:25], off offset:-1024
	global_load_dwordx4 v[106:109], v[24:25], off
	global_load_dwordx4 v[110:113], v[24:25], off offset:1024
	v_lshl_add_u64 v[70:71], v[26:27], 0, s[6:7]
	s_waitcnt vmcnt(24)
	v_mov_b32_e32 v80, v115
	v_mov_b32_e32 v81, v119
	v_mov_b32_e32 v78, v114
	v_mov_b32_e32 v79, v118
	v_pk_mul_f32 v[80:81], v[80:81], v[80:81]
	v_mov_b32_e32 v74, v116
	v_mov_b32_e32 v75, v120
	v_pk_fma_f32 v[78:79], v[78:79], v[78:79], v[80:81]
	v_mov_b32_e32 v76, v117
	v_mov_b32_e32 v77, v121
	v_pk_fma_f32 v[74:75], v[74:75], v[74:75], v[78:79]
	s_nop 0
	v_pk_fma_f32 v[72:73], v[76:77], v[76:77], v[74:75]
	s_nop 0
	v_add_f32_e32 v53, v72, v73
	v_mov_b32_e32 v80, v123
	v_mov_b32_e32 v81, v127
	v_mov_b32_e32 v78, v122
	v_mov_b32_e32 v79, v126
	v_pk_mul_f32 v[80:81], v[80:81], v[80:81]
	v_mov_b32_e32 v74, v124
	v_mov_b32_e32 v75, v128
	v_pk_fma_f32 v[78:79], v[78:79], v[78:79], v[80:81]
	v_mov_b32_e32 v76, v125
	v_mov_b32_e32 v77, v129
	v_pk_fma_f32 v[74:75], v[74:75], v[74:75], v[78:79]
	s_nop 0
	v_pk_fma_f32 v[74:75], v[76:77], v[76:77], v[74:75]
	s_nop 0
	v_add_f32_e32 v53, v53, v74
	v_add_f32_e32 v53, v53, v75
	ds_bpermute_b32 v72, v44, v53
	s_waitcnt lgkmcnt(0)
	v_add_f32_e32 v53, v53, v72
	ds_bpermute_b32 v72, v45, v53
	s_waitcnt lgkmcnt(0)
	v_add_f32_e32 v53, v53, v72
	ds_bpermute_b32 v72, v46, v53
	s_waitcnt lgkmcnt(0)
	v_add_f32_e32 v53, v53, v72
	ds_bpermute_b32 v72, v47, v53
	s_waitcnt lgkmcnt(0)
	v_add_f32_e32 v53, v53, v72
	ds_bpermute_b32 v72, v48, v53
	s_waitcnt lgkmcnt(0)
	v_add_f32_e32 v53, v53, v72
	ds_bpermute_b32 v72, v49, v53
	s_waitcnt lgkmcnt(0)
	v_add_f32_e32 v53, v53, v72
	v_fmamk_f32 v53, v53, 0x3a800000, v149
	v_cmp_gt_f32_e32 vcc, s26, v53
	v_mul_f32_e32 v72, 0x4b800000, v53
	s_nop 0
	v_cndmask_b32_e32 v53, v53, v72, vcc
	v_rsq_f32_e32 v53, v53
	s_nop 0
	v_mul_f32_e32 v72, 0x45800000, v53
	v_cndmask_b32_e32 v72, v53, v72, vcc
	v_pk_mul_f32 v[114:115], v[72:73], v[114:115] op_sel_hi:[0,1]
	v_pk_mul_f32 v[116:117], v[72:73], v[116:117] op_sel_hi:[0,1]
	v_pk_fma_f32 v[114:115], v[114:115], v[28:29], v[2:3]
	v_pk_fma_f32 v[116:117], v[116:117], v[30:31], v[4:5]
	v_cvt_pk_bf16_f32 v114, v114, v115
	v_cvt_pk_bf16_f32 v115, v116, v117
	global_store_dwordx2 v[70:71], v[114:115], off offset:-1024
	v_pk_mul_f32 v[114:115], v[72:73], v[118:119] op_sel_hi:[0,1]
	v_pk_mul_f32 v[116:117], v[72:73], v[120:121] op_sel_hi:[0,1]
	v_pk_fma_f32 v[114:115], v[114:115], v[32:33], v[6:7]
	v_pk_fma_f32 v[116:117], v[116:117], v[34:35], v[8:9]
	v_cvt_pk_bf16_f32 v114, v114, v115
	v_cvt_pk_bf16_f32 v115, v116, v117
	global_store_dwordx2 v[70:71], v[114:115], off offset:-512
	v_pk_mul_f32 v[114:115], v[72:73], v[122:123] op_sel_hi:[0,1]
	v_pk_mul_f32 v[116:117], v[72:73], v[124:125] op_sel_hi:[0,1]
	v_pk_fma_f32 v[114:115], v[114:115], v[36:37], v[10:11]
	v_pk_fma_f32 v[116:117], v[116:117], v[38:39], v[12:13]
	v_cvt_pk_bf16_f32 v114, v114, v115
	v_cvt_pk_bf16_f32 v115, v116, v117
	global_store_dwordx2 v[70:71], v[114:115], off
	v_pk_mul_f32 v[114:115], v[72:73], v[126:127] op_sel_hi:[0,1]
	v_pk_mul_f32 v[116:117], v[72:73], v[128:129] op_sel_hi:[0,1]
	v_pk_fma_f32 v[114:115], v[114:115], v[40:41], v[14:15]
	v_pk_fma_f32 v[116:117], v[116:117], v[42:43], v[16:17]
	v_cvt_pk_bf16_f32 v114, v114, v115
	v_cvt_pk_bf16_f32 v115, v116, v117
	global_store_dwordx2 v[70:71], v[114:115], off offset:512
	s_add_u32 s6, s6, 0x800
	s_addc_u32 s7, s7, 0
	v_lshl_add_u64 v[24:25], v[24:25], 0, s[48:49]
	global_load_dwordx4 v[114:117], v[24:25], off offset:-2048
	global_load_dwordx4 v[118:121], v[24:25], off offset:-1024
	global_load_dwordx4 v[122:125], v[24:25], off
	global_load_dwordx4 v[126:129], v[24:25], off offset:1024
	v_lshl_add_u64 v[70:71], v[26:27], 0, s[6:7]
	s_waitcnt vmcnt(24)
	v_mov_b32_e32 v80, v55
	v_mov_b32_e32 v81, v59
	v_mov_b32_e32 v78, v54
	v_mov_b32_e32 v79, v58
	v_pk_mul_f32 v[80:81], v[80:81], v[80:81]
	v_mov_b32_e32 v74, v56
	v_mov_b32_e32 v75, v60
	v_pk_fma_f32 v[78:79], v[78:79], v[78:79], v[80:81]
	v_mov_b32_e32 v76, v57
	v_mov_b32_e32 v77, v61
	v_pk_fma_f32 v[74:75], v[74:75], v[74:75], v[78:79]
	s_nop 0
	v_pk_fma_f32 v[72:73], v[76:77], v[76:77], v[74:75]
	s_nop 0
	v_add_f32_e32 v53, v72, v73
	v_mov_b32_e32 v80, v63
	v_mov_b32_e32 v81, v67
	v_mov_b32_e32 v78, v62
	v_mov_b32_e32 v79, v66
	v_pk_mul_f32 v[80:81], v[80:81], v[80:81]
	v_mov_b32_e32 v74, v64
	v_mov_b32_e32 v75, v68
	v_pk_fma_f32 v[78:79], v[78:79], v[78:79], v[80:81]
	v_mov_b32_e32 v76, v65
	v_mov_b32_e32 v77, v69
	v_pk_fma_f32 v[74:75], v[74:75], v[74:75], v[78:79]
	s_nop 0
	v_pk_fma_f32 v[74:75], v[76:77], v[76:77], v[74:75]
	s_nop 0
	v_add_f32_e32 v53, v53, v74
	v_add_f32_e32 v53, v53, v75
	ds_bpermute_b32 v72, v44, v53
	s_waitcnt lgkmcnt(0)
	v_add_f32_e32 v53, v53, v72
	ds_bpermute_b32 v72, v45, v53
	s_waitcnt lgkmcnt(0)
	v_add_f32_e32 v53, v53, v72
	ds_bpermute_b32 v72, v46, v53
	s_waitcnt lgkmcnt(0)
	v_add_f32_e32 v53, v53, v72
	ds_bpermute_b32 v72, v47, v53
	s_waitcnt lgkmcnt(0)
	v_add_f32_e32 v53, v53, v72
	ds_bpermute_b32 v72, v48, v53
	s_waitcnt lgkmcnt(0)
	v_add_f32_e32 v53, v53, v72
	ds_bpermute_b32 v72, v49, v53
	s_waitcnt lgkmcnt(0)
	v_add_f32_e32 v53, v53, v72
	v_fmamk_f32 v53, v53, 0x3a800000, v149
	v_cmp_gt_f32_e32 vcc, s26, v53
	v_mul_f32_e32 v72, 0x4b800000, v53
	s_nop 0
	v_cndmask_b32_e32 v53, v53, v72, vcc
	v_rsq_f32_e32 v53, v53
	s_nop 0
	v_mul_f32_e32 v72, 0x45800000, v53
	v_cndmask_b32_e32 v72, v53, v72, vcc
	v_pk_mul_f32 v[54:55], v[72:73], v[54:55] op_sel_hi:[0,1]
	v_pk_mul_f32 v[56:57], v[72:73], v[56:57] op_sel_hi:[0,1]
	v_pk_fma_f32 v[54:55], v[54:55], v[28:29], v[2:3]
	v_pk_fma_f32 v[56:57], v[56:57], v[30:31], v[4:5]
	v_cvt_pk_bf16_f32 v54, v54, v55
	v_cvt_pk_bf16_f32 v55, v56, v57
	global_store_dwordx2 v[70:71], v[54:55], off offset:-1024
	v_pk_mul_f32 v[54:55], v[72:73], v[58:59] op_sel_hi:[0,1]
	v_pk_mul_f32 v[56:57], v[72:73], v[60:61] op_sel_hi:[0,1]
	v_pk_fma_f32 v[54:55], v[54:55], v[32:33], v[6:7]
	v_pk_fma_f32 v[56:57], v[56:57], v[34:35], v[8:9]
	v_cvt_pk_bf16_f32 v54, v54, v55
	v_cvt_pk_bf16_f32 v55, v56, v57
	global_store_dwordx2 v[70:71], v[54:55], off offset:-512
	v_pk_mul_f32 v[54:55], v[72:73], v[62:63] op_sel_hi:[0,1]
	v_pk_mul_f32 v[56:57], v[72:73], v[64:65] op_sel_hi:[0,1]
	v_pk_fma_f32 v[54:55], v[54:55], v[36:37], v[10:11]
	v_pk_fma_f32 v[56:57], v[56:57], v[38:39], v[12:13]
	v_cvt_pk_bf16_f32 v54, v54, v55
	v_cvt_pk_bf16_f32 v55, v56, v57
	global_store_dwordx2 v[70:71], v[54:55], off
	v_pk_mul_f32 v[54:55], v[72:73], v[66:67] op_sel_hi:[0,1]
	v_pk_mul_f32 v[56:57], v[72:73], v[68:69] op_sel_hi:[0,1]
	v_pk_fma_f32 v[54:55], v[54:55], v[40:41], v[14:15]
	v_pk_fma_f32 v[56:57], v[56:57], v[42:43], v[16:17]
	v_cvt_pk_bf16_f32 v54, v54, v55
	v_cvt_pk_bf16_f32 v55, v56, v57
	global_store_dwordx2 v[70:71], v[54:55], off offset:512
	s_add_u32 s6, s6, 0x800
	s_addc_u32 s7, s7, 0
	v_lshl_add_u64 v[24:25], v[24:25], 0, s[48:49]
	global_load_dwordx4 v[54:57], v[24:25], off offset:-2048
	global_load_dwordx4 v[58:61], v[24:25], off offset:-1024
	global_load_dwordx4 v[62:65], v[24:25], off
	global_load_dwordx4 v[66:69], v[24:25], off offset:1024
	v_lshl_add_u64 v[70:71], v[26:27], 0, s[6:7]
	s_waitcnt vmcnt(24)
	v_mov_b32_e32 v80, v83
	v_mov_b32_e32 v81, v87
	v_mov_b32_e32 v78, v82
	v_mov_b32_e32 v79, v86
	v_pk_mul_f32 v[80:81], v[80:81], v[80:81]
	v_mov_b32_e32 v74, v84
	v_mov_b32_e32 v75, v88
	v_pk_fma_f32 v[78:79], v[78:79], v[78:79], v[80:81]
	v_mov_b32_e32 v76, v85
	v_mov_b32_e32 v77, v89
	v_pk_fma_f32 v[74:75], v[74:75], v[74:75], v[78:79]
	s_nop 0
	v_pk_fma_f32 v[72:73], v[76:77], v[76:77], v[74:75]
	s_nop 0
	v_add_f32_e32 v53, v72, v73
	v_mov_b32_e32 v80, v91
	v_mov_b32_e32 v81, v95
	v_mov_b32_e32 v78, v90
	v_mov_b32_e32 v79, v94
	v_pk_mul_f32 v[80:81], v[80:81], v[80:81]
	v_mov_b32_e32 v74, v92
	v_mov_b32_e32 v75, v96
	v_pk_fma_f32 v[78:79], v[78:79], v[78:79], v[80:81]
	v_mov_b32_e32 v76, v93
	v_mov_b32_e32 v77, v97
	v_pk_fma_f32 v[74:75], v[74:75], v[74:75], v[78:79]
	s_nop 0
	v_pk_fma_f32 v[74:75], v[76:77], v[76:77], v[74:75]
	s_nop 0
	v_add_f32_e32 v53, v53, v74
	v_add_f32_e32 v53, v53, v75
	ds_bpermute_b32 v72, v44, v53
	s_waitcnt lgkmcnt(0)
	v_add_f32_e32 v53, v53, v72
	ds_bpermute_b32 v72, v45, v53
	s_waitcnt lgkmcnt(0)
	v_add_f32_e32 v53, v53, v72
	ds_bpermute_b32 v72, v46, v53
	s_waitcnt lgkmcnt(0)
	v_add_f32_e32 v53, v53, v72
	ds_bpermute_b32 v72, v47, v53
	s_waitcnt lgkmcnt(0)
	v_add_f32_e32 v53, v53, v72
	ds_bpermute_b32 v72, v48, v53
	s_waitcnt lgkmcnt(0)
	v_add_f32_e32 v53, v53, v72
	ds_bpermute_b32 v72, v49, v53
	s_waitcnt lgkmcnt(0)
	v_add_f32_e32 v53, v53, v72
	v_fmamk_f32 v53, v53, 0x3a800000, v149
	v_cmp_gt_f32_e32 vcc, s26, v53
	v_mul_f32_e32 v72, 0x4b800000, v53
	s_nop 0
	v_cndmask_b32_e32 v53, v53, v72, vcc
	v_rsq_f32_e32 v53, v53
	s_nop 0
	v_mul_f32_e32 v72, 0x45800000, v53
	v_cndmask_b32_e32 v72, v53, v72, vcc
	v_pk_mul_f32 v[82:83], v[72:73], v[82:83] op_sel_hi:[0,1]
	v_pk_mul_f32 v[84:85], v[72:73], v[84:85] op_sel_hi:[0,1]
	v_pk_fma_f32 v[82:83], v[82:83], v[28:29], v[2:3]
	v_pk_fma_f32 v[84:85], v[84:85], v[30:31], v[4:5]
	v_cvt_pk_bf16_f32 v82, v82, v83
	v_cvt_pk_bf16_f32 v83, v84, v85
	global_store_dwordx2 v[70:71], v[82:83], off offset:-1024
	v_pk_mul_f32 v[82:83], v[72:73], v[86:87] op_sel_hi:[0,1]
	v_pk_mul_f32 v[84:85], v[72:73], v[88:89] op_sel_hi:[0,1]
	v_pk_fma_f32 v[82:83], v[82:83], v[32:33], v[6:7]
	v_pk_fma_f32 v[84:85], v[84:85], v[34:35], v[8:9]
	v_cvt_pk_bf16_f32 v82, v82, v83
	v_cvt_pk_bf16_f32 v83, v84, v85
	global_store_dwordx2 v[70:71], v[82:83], off offset:-512
	v_pk_mul_f32 v[82:83], v[72:73], v[90:91] op_sel_hi:[0,1]
	v_pk_mul_f32 v[84:85], v[72:73], v[92:93] op_sel_hi:[0,1]
	v_pk_fma_f32 v[82:83], v[82:83], v[36:37], v[10:11]
	v_pk_fma_f32 v[84:85], v[84:85], v[38:39], v[12:13]
	v_cvt_pk_bf16_f32 v82, v82, v83
	v_cvt_pk_bf16_f32 v83, v84, v85
	global_store_dwordx2 v[70:71], v[82:83], off
	v_pk_mul_f32 v[82:83], v[72:73], v[94:95] op_sel_hi:[0,1]
	v_pk_mul_f32 v[84:85], v[72:73], v[96:97] op_sel_hi:[0,1]
	v_pk_fma_f32 v[82:83], v[82:83], v[40:41], v[14:15]
	v_pk_fma_f32 v[84:85], v[84:85], v[42:43], v[16:17]
	v_cvt_pk_bf16_f32 v82, v82, v83
	v_cvt_pk_bf16_f32 v83, v84, v85
	global_store_dwordx2 v[70:71], v[82:83], off offset:512
	s_add_u32 s6, s6, 0x800
	s_addc_u32 s7, s7, 0
	v_lshl_add_u64 v[24:25], v[24:25], 0, s[48:49]
	global_load_dwordx4 v[82:85], v[24:25], off offset:-2048
	global_load_dwordx4 v[86:89], v[24:25], off offset:-1024
	global_load_dwordx4 v[90:93], v[24:25], off
	global_load_dwordx4 v[94:97], v[24:25], off offset:1024
	v_lshl_add_u64 v[70:71], v[26:27], 0, s[6:7]
	s_waitcnt vmcnt(24)
	v_mov_b32_e32 v80, v99
	v_mov_b32_e32 v81, v103
	v_mov_b32_e32 v78, v98
	v_mov_b32_e32 v79, v102
	v_pk_mul_f32 v[80:81], v[80:81], v[80:81]
	v_mov_b32_e32 v74, v100
	v_mov_b32_e32 v75, v104
	v_pk_fma_f32 v[78:79], v[78:79], v[78:79], v[80:81]
	v_mov_b32_e32 v76, v101
	v_mov_b32_e32 v77, v105
	v_pk_fma_f32 v[74:75], v[74:75], v[74:75], v[78:79]
	s_nop 0
	v_pk_fma_f32 v[72:73], v[76:77], v[76:77], v[74:75]
	s_nop 0
	v_add_f32_e32 v53, v72, v73
	v_mov_b32_e32 v80, v107
	v_mov_b32_e32 v81, v111
	v_mov_b32_e32 v78, v106
	v_mov_b32_e32 v79, v110
	v_pk_mul_f32 v[80:81], v[80:81], v[80:81]
	v_mov_b32_e32 v74, v108
	v_mov_b32_e32 v75, v112
	v_pk_fma_f32 v[78:79], v[78:79], v[78:79], v[80:81]
	v_mov_b32_e32 v76, v109
	v_mov_b32_e32 v77, v113
	v_pk_fma_f32 v[74:75], v[74:75], v[74:75], v[78:79]
	s_nop 0
	v_pk_fma_f32 v[74:75], v[76:77], v[76:77], v[74:75]
	s_nop 0
	v_add_f32_e32 v53, v53, v74
	v_add_f32_e32 v53, v53, v75
	ds_bpermute_b32 v72, v44, v53
	s_waitcnt lgkmcnt(0)
	v_add_f32_e32 v53, v53, v72
	ds_bpermute_b32 v72, v45, v53
	s_waitcnt lgkmcnt(0)
	v_add_f32_e32 v53, v53, v72
	ds_bpermute_b32 v72, v46, v53
	s_waitcnt lgkmcnt(0)
	v_add_f32_e32 v53, v53, v72
	ds_bpermute_b32 v72, v47, v53
	s_waitcnt lgkmcnt(0)
	v_add_f32_e32 v53, v53, v72
	ds_bpermute_b32 v72, v48, v53
	s_waitcnt lgkmcnt(0)
	v_add_f32_e32 v53, v53, v72
	ds_bpermute_b32 v72, v49, v53
	s_waitcnt lgkmcnt(0)
	v_add_f32_e32 v53, v53, v72
	v_fmamk_f32 v53, v53, 0x3a800000, v149
	v_cmp_gt_f32_e32 vcc, s26, v53
	v_mul_f32_e32 v72, 0x4b800000, v53
	s_nop 0
	v_cndmask_b32_e32 v53, v53, v72, vcc
	v_rsq_f32_e32 v53, v53
	s_nop 0
	v_mul_f32_e32 v72, 0x45800000, v53
	v_cndmask_b32_e32 v72, v53, v72, vcc
	v_pk_mul_f32 v[98:99], v[72:73], v[98:99] op_sel_hi:[0,1]
	v_pk_mul_f32 v[100:101], v[72:73], v[100:101] op_sel_hi:[0,1]
	v_pk_fma_f32 v[98:99], v[98:99], v[28:29], v[2:3]
	v_pk_fma_f32 v[100:101], v[100:101], v[30:31], v[4:5]
	v_cvt_pk_bf16_f32 v98, v98, v99
	v_cvt_pk_bf16_f32 v99, v100, v101
	global_store_dwordx2 v[70:71], v[98:99], off offset:-1024
	v_pk_mul_f32 v[98:99], v[72:73], v[102:103] op_sel_hi:[0,1]
	v_pk_mul_f32 v[100:101], v[72:73], v[104:105] op_sel_hi:[0,1]
	v_pk_fma_f32 v[98:99], v[98:99], v[32:33], v[6:7]
	v_pk_fma_f32 v[100:101], v[100:101], v[34:35], v[8:9]
	v_cvt_pk_bf16_f32 v98, v98, v99
	v_cvt_pk_bf16_f32 v99, v100, v101
	global_store_dwordx2 v[70:71], v[98:99], off offset:-512
	v_pk_mul_f32 v[98:99], v[72:73], v[106:107] op_sel_hi:[0,1]
	v_pk_mul_f32 v[100:101], v[72:73], v[108:109] op_sel_hi:[0,1]
	v_pk_fma_f32 v[98:99], v[98:99], v[36:37], v[10:11]
	v_pk_fma_f32 v[100:101], v[100:101], v[38:39], v[12:13]
	v_cvt_pk_bf16_f32 v98, v98, v99
	v_cvt_pk_bf16_f32 v99, v100, v101
	global_store_dwordx2 v[70:71], v[98:99], off
	v_pk_mul_f32 v[98:99], v[72:73], v[110:111] op_sel_hi:[0,1]
	v_pk_mul_f32 v[100:101], v[72:73], v[112:113] op_sel_hi:[0,1]
	v_pk_fma_f32 v[98:99], v[98:99], v[40:41], v[14:15]
	v_pk_fma_f32 v[100:101], v[100:101], v[42:43], v[16:17]
	v_cvt_pk_bf16_f32 v98, v98, v99
	v_cvt_pk_bf16_f32 v99, v100, v101
	global_store_dwordx2 v[70:71], v[98:99], off offset:512
	s_add_u32 s6, s6, 0x800
	s_addc_u32 s7, s7, 0
	v_lshl_add_u64 v[24:25], v[24:25], 0, s[48:49]
	global_load_dwordx4 v[98:101], v[24:25], off offset:-2048
	global_load_dwordx4 v[102:105], v[24:25], off offset:-1024
	global_load_dwordx4 v[106:109], v[24:25], off
	global_load_dwordx4 v[110:113], v[24:25], off offset:1024
	v_lshl_add_u64 v[70:71], v[26:27], 0, s[6:7]
	s_waitcnt vmcnt(24)
	v_mov_b32_e32 v80, v115
	v_mov_b32_e32 v81, v119
	v_mov_b32_e32 v78, v114
	v_mov_b32_e32 v79, v118
	v_pk_mul_f32 v[80:81], v[80:81], v[80:81]
	v_mov_b32_e32 v74, v116
	v_mov_b32_e32 v75, v120
	v_pk_fma_f32 v[78:79], v[78:79], v[78:79], v[80:81]
	v_mov_b32_e32 v76, v117
	v_mov_b32_e32 v77, v121
	v_pk_fma_f32 v[74:75], v[74:75], v[74:75], v[78:79]
	s_nop 0
	v_pk_fma_f32 v[72:73], v[76:77], v[76:77], v[74:75]
	s_nop 0
	v_add_f32_e32 v53, v72, v73
	v_mov_b32_e32 v80, v123
	v_mov_b32_e32 v81, v127
	v_mov_b32_e32 v78, v122
	v_mov_b32_e32 v79, v126
	v_pk_mul_f32 v[80:81], v[80:81], v[80:81]
	v_mov_b32_e32 v74, v124
	v_mov_b32_e32 v75, v128
	v_pk_fma_f32 v[78:79], v[78:79], v[78:79], v[80:81]
	v_mov_b32_e32 v76, v125
	v_mov_b32_e32 v77, v129
	v_pk_fma_f32 v[74:75], v[74:75], v[74:75], v[78:79]
	s_nop 0
	v_pk_fma_f32 v[74:75], v[76:77], v[76:77], v[74:75]
	s_nop 0
	v_add_f32_e32 v53, v53, v74
	v_add_f32_e32 v53, v53, v75
	ds_bpermute_b32 v72, v44, v53
	s_waitcnt lgkmcnt(0)
	v_add_f32_e32 v53, v53, v72
	ds_bpermute_b32 v72, v45, v53
	s_waitcnt lgkmcnt(0)
	v_add_f32_e32 v53, v53, v72
	ds_bpermute_b32 v72, v46, v53
	s_waitcnt lgkmcnt(0)
	v_add_f32_e32 v53, v53, v72
	ds_bpermute_b32 v72, v47, v53
	s_waitcnt lgkmcnt(0)
	v_add_f32_e32 v53, v53, v72
	ds_bpermute_b32 v72, v48, v53
	s_waitcnt lgkmcnt(0)
	v_add_f32_e32 v53, v53, v72
	ds_bpermute_b32 v72, v49, v53
	s_waitcnt lgkmcnt(0)
	v_add_f32_e32 v53, v53, v72
	v_fmamk_f32 v53, v53, 0x3a800000, v149
	v_cmp_gt_f32_e32 vcc, s26, v53
	v_mul_f32_e32 v72, 0x4b800000, v53
	s_nop 0
	v_cndmask_b32_e32 v53, v53, v72, vcc
	v_rsq_f32_e32 v53, v53
	s_nop 0
	v_mul_f32_e32 v72, 0x45800000, v53
	v_cndmask_b32_e32 v72, v53, v72, vcc
	v_pk_mul_f32 v[114:115], v[72:73], v[114:115] op_sel_hi:[0,1]
	v_pk_mul_f32 v[116:117], v[72:73], v[116:117] op_sel_hi:[0,1]
	v_pk_fma_f32 v[114:115], v[114:115], v[28:29], v[2:3]
	v_pk_fma_f32 v[116:117], v[116:117], v[30:31], v[4:5]
	v_cvt_pk_bf16_f32 v114, v114, v115
	v_cvt_pk_bf16_f32 v115, v116, v117
	global_store_dwordx2 v[70:71], v[114:115], off offset:-1024
	v_pk_mul_f32 v[114:115], v[72:73], v[118:119] op_sel_hi:[0,1]
	v_pk_mul_f32 v[116:117], v[72:73], v[120:121] op_sel_hi:[0,1]
	v_pk_fma_f32 v[114:115], v[114:115], v[32:33], v[6:7]
	v_pk_fma_f32 v[116:117], v[116:117], v[34:35], v[8:9]
	v_cvt_pk_bf16_f32 v114, v114, v115
	v_cvt_pk_bf16_f32 v115, v116, v117
	global_store_dwordx2 v[70:71], v[114:115], off offset:-512
	v_pk_mul_f32 v[114:115], v[72:73], v[122:123] op_sel_hi:[0,1]
	v_pk_mul_f32 v[116:117], v[72:73], v[124:125] op_sel_hi:[0,1]
	v_pk_fma_f32 v[114:115], v[114:115], v[36:37], v[10:11]
	v_pk_fma_f32 v[116:117], v[116:117], v[38:39], v[12:13]
	v_cvt_pk_bf16_f32 v114, v114, v115
	v_cvt_pk_bf16_f32 v115, v116, v117
	global_store_dwordx2 v[70:71], v[114:115], off
	v_pk_mul_f32 v[114:115], v[72:73], v[126:127] op_sel_hi:[0,1]
	v_pk_mul_f32 v[116:117], v[72:73], v[128:129] op_sel_hi:[0,1]
	v_pk_fma_f32 v[114:115], v[114:115], v[40:41], v[14:15]
	v_pk_fma_f32 v[116:117], v[116:117], v[42:43], v[16:17]
	v_cvt_pk_bf16_f32 v114, v114, v115
	v_cvt_pk_bf16_f32 v115, v116, v117
	global_store_dwordx2 v[70:71], v[114:115], off offset:512
	s_add_u32 s6, s6, 0x800
	s_addc_u32 s7, s7, 0
	v_lshl_add_u64 v[24:25], v[24:25], 0, s[48:49]
	global_load_dwordx4 v[114:117], v[24:25], off offset:-2048
	global_load_dwordx4 v[118:121], v[24:25], off offset:-1024
	global_load_dwordx4 v[122:125], v[24:25], off
	global_load_dwordx4 v[126:129], v[24:25], off offset:1024
	v_lshl_add_u64 v[70:71], v[26:27], 0, s[6:7]
	s_waitcnt vmcnt(24)
	v_mov_b32_e32 v80, v55
	v_mov_b32_e32 v81, v59
	v_mov_b32_e32 v78, v54
	v_mov_b32_e32 v79, v58
	v_pk_mul_f32 v[80:81], v[80:81], v[80:81]
	v_mov_b32_e32 v74, v56
	v_mov_b32_e32 v75, v60
	v_pk_fma_f32 v[78:79], v[78:79], v[78:79], v[80:81]
	v_mov_b32_e32 v76, v57
	v_mov_b32_e32 v77, v61
	v_pk_fma_f32 v[74:75], v[74:75], v[74:75], v[78:79]
	s_nop 0
	v_pk_fma_f32 v[72:73], v[76:77], v[76:77], v[74:75]
	s_nop 0
	v_add_f32_e32 v53, v72, v73
	v_mov_b32_e32 v80, v63
	v_mov_b32_e32 v81, v67
	v_mov_b32_e32 v78, v62
	v_mov_b32_e32 v79, v66
	v_pk_mul_f32 v[80:81], v[80:81], v[80:81]
	v_mov_b32_e32 v74, v64
	v_mov_b32_e32 v75, v68
	v_pk_fma_f32 v[78:79], v[78:79], v[78:79], v[80:81]
	v_mov_b32_e32 v76, v65
	v_mov_b32_e32 v77, v69
	v_pk_fma_f32 v[74:75], v[74:75], v[74:75], v[78:79]
	s_nop 0
	v_pk_fma_f32 v[74:75], v[76:77], v[76:77], v[74:75]
	s_nop 0
	v_add_f32_e32 v53, v53, v74
	v_add_f32_e32 v53, v53, v75
	ds_bpermute_b32 v72, v44, v53
	s_waitcnt lgkmcnt(0)
	v_add_f32_e32 v53, v53, v72
	ds_bpermute_b32 v72, v45, v53
	s_waitcnt lgkmcnt(0)
	v_add_f32_e32 v53, v53, v72
	ds_bpermute_b32 v72, v46, v53
	s_waitcnt lgkmcnt(0)
	v_add_f32_e32 v53, v53, v72
	ds_bpermute_b32 v72, v47, v53
	s_waitcnt lgkmcnt(0)
	v_add_f32_e32 v53, v53, v72
	ds_bpermute_b32 v72, v48, v53
	s_waitcnt lgkmcnt(0)
	v_add_f32_e32 v53, v53, v72
	ds_bpermute_b32 v72, v49, v53
	s_waitcnt lgkmcnt(0)
	v_add_f32_e32 v53, v53, v72
	v_fmamk_f32 v53, v53, 0x3a800000, v149
	v_cmp_gt_f32_e32 vcc, s26, v53
	v_mul_f32_e32 v72, 0x4b800000, v53
	s_nop 0
	v_cndmask_b32_e32 v53, v53, v72, vcc
	v_rsq_f32_e32 v53, v53
	s_nop 0
	v_mul_f32_e32 v72, 0x45800000, v53
	v_cndmask_b32_e32 v72, v53, v72, vcc
	v_pk_mul_f32 v[54:55], v[72:73], v[54:55] op_sel_hi:[0,1]
	v_pk_mul_f32 v[56:57], v[72:73], v[56:57] op_sel_hi:[0,1]
	v_pk_fma_f32 v[54:55], v[54:55], v[28:29], v[2:3]
	v_pk_fma_f32 v[56:57], v[56:57], v[30:31], v[4:5]
	v_cvt_pk_bf16_f32 v54, v54, v55
	v_cvt_pk_bf16_f32 v55, v56, v57
	global_store_dwordx2 v[70:71], v[54:55], off offset:-1024
	v_pk_mul_f32 v[54:55], v[72:73], v[58:59] op_sel_hi:[0,1]
	v_pk_mul_f32 v[56:57], v[72:73], v[60:61] op_sel_hi:[0,1]
	v_pk_fma_f32 v[54:55], v[54:55], v[32:33], v[6:7]
	v_pk_fma_f32 v[56:57], v[56:57], v[34:35], v[8:9]
	v_cvt_pk_bf16_f32 v54, v54, v55
	v_cvt_pk_bf16_f32 v55, v56, v57
	global_store_dwordx2 v[70:71], v[54:55], off offset:-512
	v_pk_mul_f32 v[54:55], v[72:73], v[62:63] op_sel_hi:[0,1]
	v_pk_mul_f32 v[56:57], v[72:73], v[64:65] op_sel_hi:[0,1]
	v_pk_fma_f32 v[54:55], v[54:55], v[36:37], v[10:11]
	v_pk_fma_f32 v[56:57], v[56:57], v[38:39], v[12:13]
	v_cvt_pk_bf16_f32 v54, v54, v55
	v_cvt_pk_bf16_f32 v55, v56, v57
	global_store_dwordx2 v[70:71], v[54:55], off
	v_pk_mul_f32 v[54:55], v[72:73], v[66:67] op_sel_hi:[0,1]
	v_pk_mul_f32 v[56:57], v[72:73], v[68:69] op_sel_hi:[0,1]
	v_pk_fma_f32 v[54:55], v[54:55], v[40:41], v[14:15]
	v_pk_fma_f32 v[56:57], v[56:57], v[42:43], v[16:17]
	v_cvt_pk_bf16_f32 v54, v54, v55
	v_cvt_pk_bf16_f32 v55, v56, v57
	global_store_dwordx2 v[70:71], v[54:55], off offset:512
	s_add_u32 s6, s6, 0x800
	s_addc_u32 s7, s7, 0
	v_lshl_add_u64 v[24:25], v[24:25], 0, s[48:49]
	global_load_dwordx4 v[54:57], v[24:25], off offset:-2048
	global_load_dwordx4 v[58:61], v[24:25], off offset:-1024
	global_load_dwordx4 v[62:65], v[24:25], off
	global_load_dwordx4 v[66:69], v[24:25], off offset:1024
	v_lshl_add_u64 v[70:71], v[26:27], 0, s[6:7]
	s_waitcnt vmcnt(24)
	v_mov_b32_e32 v80, v83
	v_mov_b32_e32 v81, v87
	v_mov_b32_e32 v78, v82
	v_mov_b32_e32 v79, v86
	v_pk_mul_f32 v[80:81], v[80:81], v[80:81]
	v_mov_b32_e32 v74, v84
	v_mov_b32_e32 v75, v88
	v_pk_fma_f32 v[78:79], v[78:79], v[78:79], v[80:81]
	v_mov_b32_e32 v76, v85
	v_mov_b32_e32 v77, v89
	v_pk_fma_f32 v[74:75], v[74:75], v[74:75], v[78:79]
	s_nop 0
	v_pk_fma_f32 v[72:73], v[76:77], v[76:77], v[74:75]
	s_nop 0
	v_add_f32_e32 v53, v72, v73
	v_mov_b32_e32 v80, v91
	v_mov_b32_e32 v81, v95
	v_mov_b32_e32 v78, v90
	v_mov_b32_e32 v79, v94
	v_pk_mul_f32 v[80:81], v[80:81], v[80:81]
	v_mov_b32_e32 v74, v92
	v_mov_b32_e32 v75, v96
	v_pk_fma_f32 v[78:79], v[78:79], v[78:79], v[80:81]
	v_mov_b32_e32 v76, v93
	v_mov_b32_e32 v77, v97
	v_pk_fma_f32 v[74:75], v[74:75], v[74:75], v[78:79]
	s_nop 0
	v_pk_fma_f32 v[74:75], v[76:77], v[76:77], v[74:75]
	s_nop 0
	v_add_f32_e32 v53, v53, v74
	v_add_f32_e32 v53, v53, v75
	ds_bpermute_b32 v72, v44, v53
	s_waitcnt lgkmcnt(0)
	v_add_f32_e32 v53, v53, v72
	ds_bpermute_b32 v72, v45, v53
	s_waitcnt lgkmcnt(0)
	v_add_f32_e32 v53, v53, v72
	ds_bpermute_b32 v72, v46, v53
	s_waitcnt lgkmcnt(0)
	v_add_f32_e32 v53, v53, v72
	ds_bpermute_b32 v72, v47, v53
	s_waitcnt lgkmcnt(0)
	v_add_f32_e32 v53, v53, v72
	ds_bpermute_b32 v72, v48, v53
	s_waitcnt lgkmcnt(0)
	v_add_f32_e32 v53, v53, v72
	ds_bpermute_b32 v72, v49, v53
	s_waitcnt lgkmcnt(0)
	v_add_f32_e32 v53, v53, v72
	v_fmamk_f32 v53, v53, 0x3a800000, v149
	v_cmp_gt_f32_e32 vcc, s26, v53
	v_mul_f32_e32 v72, 0x4b800000, v53
	s_nop 0
	v_cndmask_b32_e32 v53, v53, v72, vcc
	v_rsq_f32_e32 v53, v53
	s_nop 0
	v_mul_f32_e32 v72, 0x45800000, v53
	v_cndmask_b32_e32 v72, v53, v72, vcc
	v_pk_mul_f32 v[82:83], v[72:73], v[82:83] op_sel_hi:[0,1]
	v_pk_mul_f32 v[84:85], v[72:73], v[84:85] op_sel_hi:[0,1]
	v_pk_fma_f32 v[82:83], v[82:83], v[28:29], v[2:3]
	v_pk_fma_f32 v[84:85], v[84:85], v[30:31], v[4:5]
	v_cvt_pk_bf16_f32 v82, v82, v83
	v_cvt_pk_bf16_f32 v83, v84, v85
	global_store_dwordx2 v[70:71], v[82:83], off offset:-1024
	v_pk_mul_f32 v[82:83], v[72:73], v[86:87] op_sel_hi:[0,1]
	v_pk_mul_f32 v[84:85], v[72:73], v[88:89] op_sel_hi:[0,1]
	v_pk_fma_f32 v[82:83], v[82:83], v[32:33], v[6:7]
	v_pk_fma_f32 v[84:85], v[84:85], v[34:35], v[8:9]
	v_cvt_pk_bf16_f32 v82, v82, v83
	v_cvt_pk_bf16_f32 v83, v84, v85
	global_store_dwordx2 v[70:71], v[82:83], off offset:-512
	v_pk_mul_f32 v[82:83], v[72:73], v[90:91] op_sel_hi:[0,1]
	v_pk_mul_f32 v[84:85], v[72:73], v[92:93] op_sel_hi:[0,1]
	v_pk_fma_f32 v[82:83], v[82:83], v[36:37], v[10:11]
	v_pk_fma_f32 v[84:85], v[84:85], v[38:39], v[12:13]
	v_cvt_pk_bf16_f32 v82, v82, v83
	v_cvt_pk_bf16_f32 v83, v84, v85
	global_store_dwordx2 v[70:71], v[82:83], off
	v_pk_mul_f32 v[82:83], v[72:73], v[94:95] op_sel_hi:[0,1]
	v_pk_mul_f32 v[84:85], v[72:73], v[96:97] op_sel_hi:[0,1]
	v_pk_fma_f32 v[82:83], v[82:83], v[40:41], v[14:15]
	v_pk_fma_f32 v[84:85], v[84:85], v[42:43], v[16:17]
	v_cvt_pk_bf16_f32 v82, v82, v83
	v_cvt_pk_bf16_f32 v83, v84, v85
	global_store_dwordx2 v[70:71], v[82:83], off offset:512
	s_add_u32 s6, s6, 0x800
	s_addc_u32 s7, s7, 0
	v_lshl_add_u64 v[24:25], v[24:25], 0, s[48:49]
	global_load_dwordx4 v[82:85], v[24:25], off offset:-2048
	global_load_dwordx4 v[86:89], v[24:25], off offset:-1024
	global_load_dwordx4 v[90:93], v[24:25], off
	global_load_dwordx4 v[94:97], v[24:25], off offset:1024
	v_lshl_add_u64 v[70:71], v[26:27], 0, s[6:7]
	s_waitcnt vmcnt(24)
	v_mov_b32_e32 v80, v99
	v_mov_b32_e32 v81, v103
	v_mov_b32_e32 v78, v98
	v_mov_b32_e32 v79, v102
	v_pk_mul_f32 v[80:81], v[80:81], v[80:81]
	v_mov_b32_e32 v74, v100
	v_mov_b32_e32 v75, v104
	v_pk_fma_f32 v[78:79], v[78:79], v[78:79], v[80:81]
	v_mov_b32_e32 v76, v101
	v_mov_b32_e32 v77, v105
	v_pk_fma_f32 v[74:75], v[74:75], v[74:75], v[78:79]
	s_nop 0
	v_pk_fma_f32 v[72:73], v[76:77], v[76:77], v[74:75]
	s_nop 0
	v_add_f32_e32 v53, v72, v73
	v_mov_b32_e32 v80, v107
	v_mov_b32_e32 v81, v111
	v_mov_b32_e32 v78, v106
	v_mov_b32_e32 v79, v110
	v_pk_mul_f32 v[80:81], v[80:81], v[80:81]
	v_mov_b32_e32 v74, v108
	v_mov_b32_e32 v75, v112
	v_pk_fma_f32 v[78:79], v[78:79], v[78:79], v[80:81]
	v_mov_b32_e32 v76, v109
	v_mov_b32_e32 v77, v113
	v_pk_fma_f32 v[74:75], v[74:75], v[74:75], v[78:79]
	s_nop 0
	v_pk_fma_f32 v[74:75], v[76:77], v[76:77], v[74:75]
	s_nop 0
	v_add_f32_e32 v53, v53, v74
	v_add_f32_e32 v53, v53, v75
	ds_bpermute_b32 v72, v44, v53
	s_waitcnt lgkmcnt(0)
	v_add_f32_e32 v53, v53, v72
	ds_bpermute_b32 v72, v45, v53
	s_waitcnt lgkmcnt(0)
	v_add_f32_e32 v53, v53, v72
	ds_bpermute_b32 v72, v46, v53
	s_waitcnt lgkmcnt(0)
	v_add_f32_e32 v53, v53, v72
	ds_bpermute_b32 v72, v47, v53
	s_waitcnt lgkmcnt(0)
	v_add_f32_e32 v53, v53, v72
	ds_bpermute_b32 v72, v48, v53
	s_waitcnt lgkmcnt(0)
	v_add_f32_e32 v53, v53, v72
	ds_bpermute_b32 v72, v49, v53
	s_waitcnt lgkmcnt(0)
	v_add_f32_e32 v53, v53, v72
	v_fmamk_f32 v53, v53, 0x3a800000, v149
	v_cmp_gt_f32_e32 vcc, s26, v53
	v_mul_f32_e32 v72, 0x4b800000, v53
	s_nop 0
	v_cndmask_b32_e32 v53, v53, v72, vcc
	v_rsq_f32_e32 v53, v53
	s_nop 0
	v_mul_f32_e32 v72, 0x45800000, v53
	v_cndmask_b32_e32 v72, v53, v72, vcc
	v_pk_mul_f32 v[98:99], v[72:73], v[98:99] op_sel_hi:[0,1]
	v_pk_mul_f32 v[100:101], v[72:73], v[100:101] op_sel_hi:[0,1]
	v_pk_fma_f32 v[98:99], v[98:99], v[28:29], v[2:3]
	v_pk_fma_f32 v[100:101], v[100:101], v[30:31], v[4:5]
	v_cvt_pk_bf16_f32 v98, v98, v99
	v_cvt_pk_bf16_f32 v99, v100, v101
	global_store_dwordx2 v[70:71], v[98:99], off offset:-1024
	v_pk_mul_f32 v[98:99], v[72:73], v[102:103] op_sel_hi:[0,1]
	v_pk_mul_f32 v[100:101], v[72:73], v[104:105] op_sel_hi:[0,1]
	v_pk_fma_f32 v[98:99], v[98:99], v[32:33], v[6:7]
	v_pk_fma_f32 v[100:101], v[100:101], v[34:35], v[8:9]
	v_cvt_pk_bf16_f32 v98, v98, v99
	v_cvt_pk_bf16_f32 v99, v100, v101
	global_store_dwordx2 v[70:71], v[98:99], off offset:-512
	v_pk_mul_f32 v[98:99], v[72:73], v[106:107] op_sel_hi:[0,1]
	v_pk_mul_f32 v[100:101], v[72:73], v[108:109] op_sel_hi:[0,1]
	v_pk_fma_f32 v[98:99], v[98:99], v[36:37], v[10:11]
	v_pk_fma_f32 v[100:101], v[100:101], v[38:39], v[12:13]
	v_cvt_pk_bf16_f32 v98, v98, v99
	v_cvt_pk_bf16_f32 v99, v100, v101
	global_store_dwordx2 v[70:71], v[98:99], off
	v_pk_mul_f32 v[98:99], v[72:73], v[110:111] op_sel_hi:[0,1]
	v_pk_mul_f32 v[100:101], v[72:73], v[112:113] op_sel_hi:[0,1]
	v_pk_fma_f32 v[98:99], v[98:99], v[40:41], v[14:15]
	v_pk_fma_f32 v[100:101], v[100:101], v[42:43], v[16:17]
	v_cvt_pk_bf16_f32 v98, v98, v99
	v_cvt_pk_bf16_f32 v99, v100, v101
	global_store_dwordx2 v[70:71], v[98:99], off offset:512
	s_add_u32 s6, s6, 0x800
	s_addc_u32 s7, s7, 0
	v_lshl_add_u64 v[24:25], v[24:25], 0, s[48:49]
	global_load_dwordx4 v[98:101], v[24:25], off offset:-2048
	global_load_dwordx4 v[102:105], v[24:25], off offset:-1024
	global_load_dwordx4 v[106:109], v[24:25], off
	global_load_dwordx4 v[110:113], v[24:25], off offset:1024
	v_lshl_add_u64 v[70:71], v[26:27], 0, s[6:7]
	s_waitcnt vmcnt(24)
	v_mov_b32_e32 v80, v115
	v_mov_b32_e32 v81, v119
	v_mov_b32_e32 v78, v114
	v_mov_b32_e32 v79, v118
	v_pk_mul_f32 v[80:81], v[80:81], v[80:81]
	v_mov_b32_e32 v74, v116
	v_mov_b32_e32 v75, v120
	v_pk_fma_f32 v[78:79], v[78:79], v[78:79], v[80:81]
	v_mov_b32_e32 v76, v117
	v_mov_b32_e32 v77, v121
	v_pk_fma_f32 v[74:75], v[74:75], v[74:75], v[78:79]
	s_nop 0
	v_pk_fma_f32 v[72:73], v[76:77], v[76:77], v[74:75]
	s_nop 0
	v_add_f32_e32 v53, v72, v73
	v_mov_b32_e32 v80, v123
	v_mov_b32_e32 v81, v127
	v_mov_b32_e32 v78, v122
	v_mov_b32_e32 v79, v126
	v_pk_mul_f32 v[80:81], v[80:81], v[80:81]
	v_mov_b32_e32 v74, v124
	v_mov_b32_e32 v75, v128
	v_pk_fma_f32 v[78:79], v[78:79], v[78:79], v[80:81]
	v_mov_b32_e32 v76, v125
	v_mov_b32_e32 v77, v129
	v_pk_fma_f32 v[74:75], v[74:75], v[74:75], v[78:79]
	s_nop 0
	v_pk_fma_f32 v[74:75], v[76:77], v[76:77], v[74:75]
	s_nop 0
	v_add_f32_e32 v53, v53, v74
	v_add_f32_e32 v53, v53, v75
	ds_bpermute_b32 v72, v44, v53
	s_waitcnt lgkmcnt(0)
	v_add_f32_e32 v53, v53, v72
	ds_bpermute_b32 v72, v45, v53
	s_waitcnt lgkmcnt(0)
	v_add_f32_e32 v53, v53, v72
	ds_bpermute_b32 v72, v46, v53
	s_waitcnt lgkmcnt(0)
	v_add_f32_e32 v53, v53, v72
	ds_bpermute_b32 v72, v47, v53
	s_waitcnt lgkmcnt(0)
	v_add_f32_e32 v53, v53, v72
	ds_bpermute_b32 v72, v48, v53
	s_waitcnt lgkmcnt(0)
	v_add_f32_e32 v53, v53, v72
	ds_bpermute_b32 v72, v49, v53
	s_waitcnt lgkmcnt(0)
	v_add_f32_e32 v53, v53, v72
	v_fmamk_f32 v53, v53, 0x3a800000, v149
	v_cmp_gt_f32_e32 vcc, s26, v53
	v_mul_f32_e32 v72, 0x4b800000, v53
	s_nop 0
	v_cndmask_b32_e32 v53, v53, v72, vcc
	v_rsq_f32_e32 v53, v53
	s_nop 0
	v_mul_f32_e32 v72, 0x45800000, v53
	v_cndmask_b32_e32 v72, v53, v72, vcc
	v_pk_mul_f32 v[114:115], v[72:73], v[114:115] op_sel_hi:[0,1]
	v_pk_mul_f32 v[116:117], v[72:73], v[116:117] op_sel_hi:[0,1]
	v_pk_fma_f32 v[114:115], v[114:115], v[28:29], v[2:3]
	v_pk_fma_f32 v[116:117], v[116:117], v[30:31], v[4:5]
	v_cvt_pk_bf16_f32 v114, v114, v115
	v_cvt_pk_bf16_f32 v115, v116, v117
	global_store_dwordx2 v[70:71], v[114:115], off offset:-1024
	v_pk_mul_f32 v[114:115], v[72:73], v[118:119] op_sel_hi:[0,1]
	v_pk_mul_f32 v[116:117], v[72:73], v[120:121] op_sel_hi:[0,1]
	v_pk_fma_f32 v[114:115], v[114:115], v[32:33], v[6:7]
	v_pk_fma_f32 v[116:117], v[116:117], v[34:35], v[8:9]
	v_cvt_pk_bf16_f32 v114, v114, v115
	v_cvt_pk_bf16_f32 v115, v116, v117
	global_store_dwordx2 v[70:71], v[114:115], off offset:-512
	v_pk_mul_f32 v[114:115], v[72:73], v[122:123] op_sel_hi:[0,1]
	v_pk_mul_f32 v[116:117], v[72:73], v[124:125] op_sel_hi:[0,1]
	v_pk_fma_f32 v[114:115], v[114:115], v[36:37], v[10:11]
	v_pk_fma_f32 v[116:117], v[116:117], v[38:39], v[12:13]
	v_cvt_pk_bf16_f32 v114, v114, v115
	v_cvt_pk_bf16_f32 v115, v116, v117
	global_store_dwordx2 v[70:71], v[114:115], off
	v_pk_mul_f32 v[114:115], v[72:73], v[126:127] op_sel_hi:[0,1]
	v_pk_mul_f32 v[116:117], v[72:73], v[128:129] op_sel_hi:[0,1]
	v_pk_fma_f32 v[114:115], v[114:115], v[40:41], v[14:15]
	v_pk_fma_f32 v[116:117], v[116:117], v[42:43], v[16:17]
	v_cvt_pk_bf16_f32 v114, v114, v115
	v_cvt_pk_bf16_f32 v115, v116, v117
	global_store_dwordx2 v[70:71], v[114:115], off offset:512
	s_add_u32 s6, s6, 0x800
	s_addc_u32 s7, s7, 0
	v_lshl_add_u64 v[24:25], v[24:25], 0, s[48:49]
	global_load_dwordx4 v[114:117], v[24:25], off offset:-2048
	global_load_dwordx4 v[118:121], v[24:25], off offset:-1024
	global_load_dwordx4 v[122:125], v[24:25], off
	global_load_dwordx4 v[126:129], v[24:25], off offset:1024
	v_lshl_add_u64 v[70:71], v[26:27], 0, s[6:7]
	s_waitcnt vmcnt(24)
	v_mov_b32_e32 v80, v55
	v_mov_b32_e32 v81, v59
	v_mov_b32_e32 v78, v54
	v_mov_b32_e32 v79, v58
	v_pk_mul_f32 v[80:81], v[80:81], v[80:81]
	v_mov_b32_e32 v74, v56
	v_mov_b32_e32 v75, v60
	v_pk_fma_f32 v[78:79], v[78:79], v[78:79], v[80:81]
	v_mov_b32_e32 v76, v57
	v_mov_b32_e32 v77, v61
	v_pk_fma_f32 v[74:75], v[74:75], v[74:75], v[78:79]
	s_nop 0
	v_pk_fma_f32 v[72:73], v[76:77], v[76:77], v[74:75]
	s_nop 0
	v_add_f32_e32 v53, v72, v73
	v_mov_b32_e32 v80, v63
	v_mov_b32_e32 v81, v67
	v_mov_b32_e32 v78, v62
	v_mov_b32_e32 v79, v66
	v_pk_mul_f32 v[80:81], v[80:81], v[80:81]
	v_mov_b32_e32 v74, v64
	v_mov_b32_e32 v75, v68
	v_pk_fma_f32 v[78:79], v[78:79], v[78:79], v[80:81]
	v_mov_b32_e32 v76, v65
	v_mov_b32_e32 v77, v69
	v_pk_fma_f32 v[74:75], v[74:75], v[74:75], v[78:79]
	s_nop 0
	v_pk_fma_f32 v[74:75], v[76:77], v[76:77], v[74:75]
	s_nop 0
	v_add_f32_e32 v53, v53, v74
	v_add_f32_e32 v53, v53, v75
	ds_bpermute_b32 v72, v44, v53
	s_waitcnt lgkmcnt(0)
	v_add_f32_e32 v53, v53, v72
	ds_bpermute_b32 v72, v45, v53
	s_waitcnt lgkmcnt(0)
	v_add_f32_e32 v53, v53, v72
	ds_bpermute_b32 v72, v46, v53
	s_waitcnt lgkmcnt(0)
	v_add_f32_e32 v53, v53, v72
	ds_bpermute_b32 v72, v47, v53
	s_waitcnt lgkmcnt(0)
	v_add_f32_e32 v53, v53, v72
	ds_bpermute_b32 v72, v48, v53
	s_waitcnt lgkmcnt(0)
	v_add_f32_e32 v53, v53, v72
	ds_bpermute_b32 v72, v49, v53
	s_waitcnt lgkmcnt(0)
	v_add_f32_e32 v53, v53, v72
	v_fmamk_f32 v53, v53, 0x3a800000, v149
	v_cmp_gt_f32_e32 vcc, s26, v53
	v_mul_f32_e32 v72, 0x4b800000, v53
	s_nop 0
	v_cndmask_b32_e32 v53, v53, v72, vcc
	v_rsq_f32_e32 v53, v53
	s_nop 0
	v_mul_f32_e32 v72, 0x45800000, v53
	v_cndmask_b32_e32 v72, v53, v72, vcc
	v_pk_mul_f32 v[54:55], v[72:73], v[54:55] op_sel_hi:[0,1]
	v_pk_mul_f32 v[56:57], v[72:73], v[56:57] op_sel_hi:[0,1]
	v_pk_fma_f32 v[54:55], v[54:55], v[28:29], v[2:3]
	v_pk_fma_f32 v[56:57], v[56:57], v[30:31], v[4:5]
	v_cvt_pk_bf16_f32 v54, v54, v55
	v_cvt_pk_bf16_f32 v55, v56, v57
	global_store_dwordx2 v[70:71], v[54:55], off offset:-1024
	v_pk_mul_f32 v[54:55], v[72:73], v[58:59] op_sel_hi:[0,1]
	v_pk_mul_f32 v[56:57], v[72:73], v[60:61] op_sel_hi:[0,1]
	v_pk_fma_f32 v[54:55], v[54:55], v[32:33], v[6:7]
	v_pk_fma_f32 v[56:57], v[56:57], v[34:35], v[8:9]
	v_cvt_pk_bf16_f32 v54, v54, v55
	v_cvt_pk_bf16_f32 v55, v56, v57
	global_store_dwordx2 v[70:71], v[54:55], off offset:-512
	v_pk_mul_f32 v[54:55], v[72:73], v[62:63] op_sel_hi:[0,1]
	v_pk_mul_f32 v[56:57], v[72:73], v[64:65] op_sel_hi:[0,1]
	v_pk_fma_f32 v[54:55], v[54:55], v[36:37], v[10:11]
	v_pk_fma_f32 v[56:57], v[56:57], v[38:39], v[12:13]
	v_cvt_pk_bf16_f32 v54, v54, v55
	v_cvt_pk_bf16_f32 v55, v56, v57
	global_store_dwordx2 v[70:71], v[54:55], off
	v_pk_mul_f32 v[54:55], v[72:73], v[66:67] op_sel_hi:[0,1]
	v_pk_mul_f32 v[56:57], v[72:73], v[68:69] op_sel_hi:[0,1]
	v_pk_fma_f32 v[54:55], v[54:55], v[40:41], v[14:15]
	v_pk_fma_f32 v[56:57], v[56:57], v[42:43], v[16:17]
	v_cvt_pk_bf16_f32 v54, v54, v55
	v_cvt_pk_bf16_f32 v55, v56, v57
	global_store_dwordx2 v[70:71], v[54:55], off offset:512
	s_add_u32 s6, s6, 0x800
	s_addc_u32 s7, s7, 0
	v_lshl_add_u64 v[70:71], v[26:27], 0, s[6:7]
	s_waitcnt vmcnt(20)
	v_mov_b32_e32 v80, v83
	v_mov_b32_e32 v81, v87
	v_mov_b32_e32 v78, v82
	v_mov_b32_e32 v79, v86
	v_pk_mul_f32 v[80:81], v[80:81], v[80:81]
	v_mov_b32_e32 v74, v84
	v_mov_b32_e32 v75, v88
	v_pk_fma_f32 v[78:79], v[78:79], v[78:79], v[80:81]
	v_mov_b32_e32 v76, v85
	v_mov_b32_e32 v77, v89
	v_pk_fma_f32 v[74:75], v[74:75], v[74:75], v[78:79]
	s_nop 0
	v_pk_fma_f32 v[72:73], v[76:77], v[76:77], v[74:75]
	s_nop 0
	v_add_f32_e32 v53, v72, v73
	v_mov_b32_e32 v80, v91
	v_mov_b32_e32 v81, v95
	v_mov_b32_e32 v78, v90
	v_mov_b32_e32 v79, v94
	v_pk_mul_f32 v[80:81], v[80:81], v[80:81]
	v_mov_b32_e32 v74, v92
	v_mov_b32_e32 v75, v96
	v_pk_fma_f32 v[78:79], v[78:79], v[78:79], v[80:81]
	v_mov_b32_e32 v76, v93
	v_mov_b32_e32 v77, v97
	v_pk_fma_f32 v[74:75], v[74:75], v[74:75], v[78:79]
	s_nop 0
	v_pk_fma_f32 v[74:75], v[76:77], v[76:77], v[74:75]
	s_nop 0
	v_add_f32_e32 v53, v53, v74
	v_add_f32_e32 v53, v53, v75
	ds_bpermute_b32 v72, v44, v53
	s_waitcnt lgkmcnt(0)
	v_add_f32_e32 v53, v53, v72
	ds_bpermute_b32 v72, v45, v53
	s_waitcnt lgkmcnt(0)
	v_add_f32_e32 v53, v53, v72
	ds_bpermute_b32 v72, v46, v53
	s_waitcnt lgkmcnt(0)
	v_add_f32_e32 v53, v53, v72
	ds_bpermute_b32 v72, v47, v53
	s_waitcnt lgkmcnt(0)
	v_add_f32_e32 v53, v53, v72
	ds_bpermute_b32 v72, v48, v53
	s_waitcnt lgkmcnt(0)
	v_add_f32_e32 v53, v53, v72
	ds_bpermute_b32 v72, v49, v53
	s_waitcnt lgkmcnt(0)
	v_add_f32_e32 v53, v53, v72
	v_fmamk_f32 v53, v53, 0x3a800000, v149
	v_cmp_gt_f32_e32 vcc, s26, v53
	v_mul_f32_e32 v72, 0x4b800000, v53
	s_nop 0
	v_cndmask_b32_e32 v53, v53, v72, vcc
	v_rsq_f32_e32 v53, v53
	s_nop 0
	v_mul_f32_e32 v72, 0x45800000, v53
	v_cndmask_b32_e32 v72, v53, v72, vcc
	v_pk_mul_f32 v[82:83], v[72:73], v[82:83] op_sel_hi:[0,1]
	v_pk_mul_f32 v[84:85], v[72:73], v[84:85] op_sel_hi:[0,1]
	v_pk_fma_f32 v[82:83], v[82:83], v[28:29], v[2:3]
	v_pk_fma_f32 v[84:85], v[84:85], v[30:31], v[4:5]
	v_cvt_pk_bf16_f32 v82, v82, v83
	v_cvt_pk_bf16_f32 v83, v84, v85
	global_store_dwordx2 v[70:71], v[82:83], off offset:-1024
	v_pk_mul_f32 v[82:83], v[72:73], v[86:87] op_sel_hi:[0,1]
	v_pk_mul_f32 v[84:85], v[72:73], v[88:89] op_sel_hi:[0,1]
	v_pk_fma_f32 v[82:83], v[82:83], v[32:33], v[6:7]
	v_pk_fma_f32 v[84:85], v[84:85], v[34:35], v[8:9]
	v_cvt_pk_bf16_f32 v82, v82, v83
	v_cvt_pk_bf16_f32 v83, v84, v85
	global_store_dwordx2 v[70:71], v[82:83], off offset:-512
	v_pk_mul_f32 v[82:83], v[72:73], v[90:91] op_sel_hi:[0,1]
	v_pk_mul_f32 v[84:85], v[72:73], v[92:93] op_sel_hi:[0,1]
	v_pk_fma_f32 v[82:83], v[82:83], v[36:37], v[10:11]
	v_pk_fma_f32 v[84:85], v[84:85], v[38:39], v[12:13]
	v_cvt_pk_bf16_f32 v82, v82, v83
	v_cvt_pk_bf16_f32 v83, v84, v85
	global_store_dwordx2 v[70:71], v[82:83], off
	v_pk_mul_f32 v[82:83], v[72:73], v[94:95] op_sel_hi:[0,1]
	v_pk_mul_f32 v[84:85], v[72:73], v[96:97] op_sel_hi:[0,1]
	v_pk_fma_f32 v[82:83], v[82:83], v[40:41], v[14:15]
	v_pk_fma_f32 v[84:85], v[84:85], v[42:43], v[16:17]
	v_cvt_pk_bf16_f32 v82, v82, v83
	v_cvt_pk_bf16_f32 v83, v84, v85
	global_store_dwordx2 v[70:71], v[82:83], off offset:512
	s_add_u32 s6, s6, 0x800
	s_addc_u32 s7, s7, 0
	v_lshl_add_u64 v[70:71], v[26:27], 0, s[6:7]
	s_waitcnt vmcnt(16)
	v_mov_b32_e32 v80, v99
	v_mov_b32_e32 v81, v103
	v_mov_b32_e32 v78, v98
	v_mov_b32_e32 v79, v102
	v_pk_mul_f32 v[80:81], v[80:81], v[80:81]
	v_mov_b32_e32 v74, v100
	v_mov_b32_e32 v75, v104
	v_pk_fma_f32 v[78:79], v[78:79], v[78:79], v[80:81]
	v_mov_b32_e32 v76, v101
	v_mov_b32_e32 v77, v105
	v_pk_fma_f32 v[74:75], v[74:75], v[74:75], v[78:79]
	s_nop 0
	v_pk_fma_f32 v[72:73], v[76:77], v[76:77], v[74:75]
	s_nop 0
	v_add_f32_e32 v53, v72, v73
	v_mov_b32_e32 v80, v107
	v_mov_b32_e32 v81, v111
	v_mov_b32_e32 v78, v106
	v_mov_b32_e32 v79, v110
	v_pk_mul_f32 v[80:81], v[80:81], v[80:81]
	v_mov_b32_e32 v74, v108
	v_mov_b32_e32 v75, v112
	v_pk_fma_f32 v[78:79], v[78:79], v[78:79], v[80:81]
	v_mov_b32_e32 v76, v109
	v_mov_b32_e32 v77, v113
	v_pk_fma_f32 v[74:75], v[74:75], v[74:75], v[78:79]
	s_nop 0
	v_pk_fma_f32 v[74:75], v[76:77], v[76:77], v[74:75]
	s_nop 0
	v_add_f32_e32 v53, v53, v74
	v_add_f32_e32 v53, v53, v75
	ds_bpermute_b32 v72, v44, v53
	s_waitcnt lgkmcnt(0)
	v_add_f32_e32 v53, v53, v72
	ds_bpermute_b32 v72, v45, v53
	s_waitcnt lgkmcnt(0)
	v_add_f32_e32 v53, v53, v72
	ds_bpermute_b32 v72, v46, v53
	s_waitcnt lgkmcnt(0)
	v_add_f32_e32 v53, v53, v72
	ds_bpermute_b32 v72, v47, v53
	s_waitcnt lgkmcnt(0)
	v_add_f32_e32 v53, v53, v72
	ds_bpermute_b32 v72, v48, v53
	s_waitcnt lgkmcnt(0)
	v_add_f32_e32 v53, v53, v72
	ds_bpermute_b32 v72, v49, v53
	s_waitcnt lgkmcnt(0)
	v_add_f32_e32 v53, v53, v72
	v_fmamk_f32 v53, v53, 0x3a800000, v149
	v_cmp_gt_f32_e32 vcc, s26, v53
	v_mul_f32_e32 v72, 0x4b800000, v53
	s_nop 0
	v_cndmask_b32_e32 v53, v53, v72, vcc
	v_rsq_f32_e32 v53, v53
	s_nop 0
	v_mul_f32_e32 v72, 0x45800000, v53
	v_cndmask_b32_e32 v72, v53, v72, vcc
	v_pk_mul_f32 v[98:99], v[72:73], v[98:99] op_sel_hi:[0,1]
	v_pk_mul_f32 v[100:101], v[72:73], v[100:101] op_sel_hi:[0,1]
	v_pk_fma_f32 v[98:99], v[98:99], v[28:29], v[2:3]
	v_pk_fma_f32 v[100:101], v[100:101], v[30:31], v[4:5]
	v_cvt_pk_bf16_f32 v98, v98, v99
	v_cvt_pk_bf16_f32 v99, v100, v101
	global_store_dwordx2 v[70:71], v[98:99], off offset:-1024
	v_pk_mul_f32 v[98:99], v[72:73], v[102:103] op_sel_hi:[0,1]
	v_pk_mul_f32 v[100:101], v[72:73], v[104:105] op_sel_hi:[0,1]
	v_pk_fma_f32 v[98:99], v[98:99], v[32:33], v[6:7]
	v_pk_fma_f32 v[100:101], v[100:101], v[34:35], v[8:9]
	v_cvt_pk_bf16_f32 v98, v98, v99
	v_cvt_pk_bf16_f32 v99, v100, v101
	global_store_dwordx2 v[70:71], v[98:99], off offset:-512
	v_pk_mul_f32 v[98:99], v[72:73], v[106:107] op_sel_hi:[0,1]
	v_pk_mul_f32 v[100:101], v[72:73], v[108:109] op_sel_hi:[0,1]
	v_pk_fma_f32 v[98:99], v[98:99], v[36:37], v[10:11]
	v_pk_fma_f32 v[100:101], v[100:101], v[38:39], v[12:13]
	v_cvt_pk_bf16_f32 v98, v98, v99
	v_cvt_pk_bf16_f32 v99, v100, v101
	global_store_dwordx2 v[70:71], v[98:99], off
	v_pk_mul_f32 v[98:99], v[72:73], v[110:111] op_sel_hi:[0,1]
	v_pk_mul_f32 v[100:101], v[72:73], v[112:113] op_sel_hi:[0,1]
	v_pk_fma_f32 v[98:99], v[98:99], v[40:41], v[14:15]
	v_pk_fma_f32 v[100:101], v[100:101], v[42:43], v[16:17]
	v_cvt_pk_bf16_f32 v98, v98, v99
	v_cvt_pk_bf16_f32 v99, v100, v101
	global_store_dwordx2 v[70:71], v[98:99], off offset:512
	s_add_u32 s6, s6, 0x800
	s_addc_u32 s7, s7, 0
	v_lshl_add_u64 v[70:71], v[26:27], 0, s[6:7]
	s_waitcnt vmcnt(12)
	v_mov_b32_e32 v80, v115
	v_mov_b32_e32 v81, v119
	v_mov_b32_e32 v78, v114
	v_mov_b32_e32 v79, v118
	v_pk_mul_f32 v[80:81], v[80:81], v[80:81]
	v_mov_b32_e32 v74, v116
	v_mov_b32_e32 v75, v120
	v_pk_fma_f32 v[78:79], v[78:79], v[78:79], v[80:81]
	v_mov_b32_e32 v76, v117
	v_mov_b32_e32 v77, v121
	v_pk_fma_f32 v[74:75], v[74:75], v[74:75], v[78:79]
	s_nop 0
	v_pk_fma_f32 v[72:73], v[76:77], v[76:77], v[74:75]
	s_nop 0
	v_add_f32_e32 v53, v72, v73
	v_mov_b32_e32 v80, v123
	v_mov_b32_e32 v81, v127
	v_mov_b32_e32 v78, v122
	v_mov_b32_e32 v79, v126
	v_pk_mul_f32 v[80:81], v[80:81], v[80:81]
	v_mov_b32_e32 v74, v124
	v_mov_b32_e32 v75, v128
	v_pk_fma_f32 v[78:79], v[78:79], v[78:79], v[80:81]
	v_mov_b32_e32 v76, v125
	v_mov_b32_e32 v77, v129
	v_pk_fma_f32 v[74:75], v[74:75], v[74:75], v[78:79]
	s_nop 0
	v_pk_fma_f32 v[74:75], v[76:77], v[76:77], v[74:75]
	s_nop 0
	v_add_f32_e32 v53, v53, v74
	v_add_f32_e32 v53, v53, v75
	ds_bpermute_b32 v72, v44, v53
	s_waitcnt lgkmcnt(0)
	v_add_f32_e32 v53, v53, v72
	ds_bpermute_b32 v72, v45, v53
	s_waitcnt lgkmcnt(0)
	v_add_f32_e32 v53, v53, v72
	ds_bpermute_b32 v72, v46, v53
	s_waitcnt lgkmcnt(0)
	v_add_f32_e32 v53, v53, v72
	ds_bpermute_b32 v72, v47, v53
	s_waitcnt lgkmcnt(0)
	v_add_f32_e32 v53, v53, v72
	ds_bpermute_b32 v72, v48, v53
	s_waitcnt lgkmcnt(0)
	v_add_f32_e32 v53, v53, v72
	ds_bpermute_b32 v72, v49, v53
	s_waitcnt lgkmcnt(0)
	v_add_f32_e32 v53, v53, v72
	v_fmamk_f32 v53, v53, 0x3a800000, v149
	v_cmp_gt_f32_e32 vcc, s26, v53
	v_mul_f32_e32 v72, 0x4b800000, v53
	s_nop 0
	v_cndmask_b32_e32 v53, v53, v72, vcc
	v_rsq_f32_e32 v53, v53
	s_nop 0
	v_mul_f32_e32 v72, 0x45800000, v53
	v_cndmask_b32_e32 v72, v53, v72, vcc
	v_pk_mul_f32 v[114:115], v[72:73], v[114:115] op_sel_hi:[0,1]
	v_pk_mul_f32 v[116:117], v[72:73], v[116:117] op_sel_hi:[0,1]
	v_pk_fma_f32 v[114:115], v[114:115], v[28:29], v[2:3]
	v_pk_fma_f32 v[116:117], v[116:117], v[30:31], v[4:5]
	v_cvt_pk_bf16_f32 v114, v114, v115
	v_cvt_pk_bf16_f32 v115, v116, v117
	global_store_dwordx2 v[70:71], v[114:115], off offset:-1024
	v_pk_mul_f32 v[114:115], v[72:73], v[118:119] op_sel_hi:[0,1]
	v_pk_mul_f32 v[116:117], v[72:73], v[120:121] op_sel_hi:[0,1]
	v_pk_fma_f32 v[114:115], v[114:115], v[32:33], v[6:7]
	v_pk_fma_f32 v[116:117], v[116:117], v[34:35], v[8:9]
	v_cvt_pk_bf16_f32 v114, v114, v115
	v_cvt_pk_bf16_f32 v115, v116, v117
	global_store_dwordx2 v[70:71], v[114:115], off offset:-512
	v_pk_mul_f32 v[114:115], v[72:73], v[122:123] op_sel_hi:[0,1]
	v_pk_mul_f32 v[116:117], v[72:73], v[124:125] op_sel_hi:[0,1]
	v_pk_fma_f32 v[114:115], v[114:115], v[36:37], v[10:11]
	v_pk_fma_f32 v[116:117], v[116:117], v[38:39], v[12:13]
	v_cvt_pk_bf16_f32 v114, v114, v115
	v_cvt_pk_bf16_f32 v115, v116, v117
	global_store_dwordx2 v[70:71], v[114:115], off
	v_pk_mul_f32 v[114:115], v[72:73], v[126:127] op_sel_hi:[0,1]
	v_pk_mul_f32 v[116:117], v[72:73], v[128:129] op_sel_hi:[0,1]
	v_pk_fma_f32 v[114:115], v[114:115], v[40:41], v[14:15]
	v_pk_fma_f32 v[116:117], v[116:117], v[42:43], v[16:17]
	v_cvt_pk_bf16_f32 v114, v114, v115
	v_cvt_pk_bf16_f32 v115, v116, v117
	global_store_dwordx2 v[70:71], v[114:115], off offset:512
	s_add_u32 s6, s6, 0x800
	s_addc_u32 s7, s7, 0
	s_add_i32 s4, s4, s3
	s_cmpk_gt_i32 s4, 0xff
	s_cbranch_scc0 .LBB0_119

.LBB0_530:
	s_ashr_i32 s5, s4, 31
	s_lshl_b64 s[0:1], s[4:5], 19
	v_lshl_add_u64 v[24:25], v[20:21], 0, s[0:1]
	s_lshl_b64 s[0:1], s[4:5], 18
	v_lshl_add_u64 v[26:27], v[22:23], 0, s[0:1]
	s_ashr_i32 s0, s4, 5
	s_mul_hi_i32 s1, s0, 0x6000
	s_mulk_i32 s0, 0x6000
	s_add_u32 s0, s10, s0
	s_addc_u32 s1, s11, s1
	s_add_u32 s6, s0, 0x4000
	s_addc_u32 s7, s1, 0
	s_add_u32 s0, s0, 0x3000
	s_addc_u32 s1, s1, 0
	global_load_dwordx4 v[28:31], v[18:19], off
	global_load_dwordx4 v[114:117], v0, s[6:7]
	global_load_dwordx4 v[2:5], v0, s[0:1]
	global_load_dwordx4 v[32:35], v[18:19], off offset:1024
	global_load_dwordx4 v[118:121], v50, s[6:7]
	global_load_dwordx4 v[6:9], v0, s[0:1] offset:1024
	global_load_dwordx4 v[36:39], v[18:19], off offset:2048
	global_load_dwordx4 v[122:125], v51, s[6:7]
	global_load_dwordx4 v[10:13], v0, s[0:1] offset:2048
	global_load_dwordx4 v[40:43], v[18:19], off offset:3072
	global_load_dwordx4 v[126:129], v52, s[6:7]
	global_load_dwordx4 v[14:17], v0, s[0:1] offset:3072
	global_load_dwordx4 v[54:57], v[24:25], off offset:-2048
	global_load_dwordx4 v[58:61], v[24:25], off offset:-1024
	global_load_dwordx4 v[62:65], v[24:25], off
	global_load_dwordx4 v[66:69], v[24:25], off offset:1024
	v_lshl_add_u64 v[24:25], v[24:25], 0, s[48:49]
	global_load_dwordx4 v[82:85], v[24:25], off offset:-2048
	global_load_dwordx4 v[86:89], v[24:25], off offset:-1024
	global_load_dwordx4 v[90:93], v[24:25], off
	global_load_dwordx4 v[94:97], v[24:25], off offset:1024
	v_lshl_add_u64 v[24:25], v[24:25], 0, s[48:49]
	global_load_dwordx4 v[98:101], v[24:25], off offset:-2048
	global_load_dwordx4 v[102:105], v[24:25], off offset:-1024
	global_load_dwordx4 v[106:109], v[24:25], off
	global_load_dwordx4 v[110:113], v[24:25], off offset:1024
	s_mov_b64 s[6:7], 0
	s_waitcnt vmcnt(12)
	v_pk_add_f32 v[114:115], v[114:115], 1.0 op_sel_hi:[1,0]
	v_pk_add_f32 v[116:117], v[116:117], 1.0 op_sel_hi:[1,0]
	v_pk_add_f32 v[118:119], v[118:119], 1.0 op_sel_hi:[1,0]
	v_pk_add_f32 v[120:121], v[120:121], 1.0 op_sel_hi:[1,0]
	v_pk_add_f32 v[122:123], v[122:123], 1.0 op_sel_hi:[1,0]
	v_pk_add_f32 v[124:125], v[124:125], 1.0 op_sel_hi:[1,0]
	v_pk_add_f32 v[126:127], v[126:127], 1.0 op_sel_hi:[1,0]
	v_pk_add_f32 v[128:129], v[128:129], 1.0 op_sel_hi:[1,0]
	v_pk_mul_f32 v[28:29], v[28:29], v[114:115]
	v_pk_mul_f32 v[30:31], v[30:31], v[116:117]
	v_pk_mul_f32 v[32:33], v[32:33], v[118:119]
	v_pk_mul_f32 v[34:35], v[34:35], v[120:121]
	v_pk_mul_f32 v[36:37], v[36:37], v[122:123]
	v_pk_mul_f32 v[38:39], v[38:39], v[124:125]
	v_pk_mul_f32 v[40:41], v[40:41], v[126:127]
	v_pk_mul_f32 v[42:43], v[42:43], v[128:129]
	v_lshl_add_u64 v[24:25], v[24:25], 0, s[48:49]
	global_load_dwordx4 v[114:117], v[24:25], off offset:-2048
	global_load_dwordx4 v[118:121], v[24:25], off offset:-1024
	global_load_dwordx4 v[122:125], v[24:25], off
	global_load_dwordx4 v[126:129], v[24:25], off offset:1024
	v_lshl_add_u64 v[70:71], v[26:27], 0, s[6:7]
	s_waitcnt vmcnt(12)
	v_mov_b32_e32 v80, v55
	v_mov_b32_e32 v81, v59
	v_mov_b32_e32 v78, v54
	v_mov_b32_e32 v79, v58
	v_pk_mul_f32 v[80:81], v[80:81], v[80:81]
	v_mov_b32_e32 v74, v56
	v_mov_b32_e32 v75, v60
	v_pk_fma_f32 v[78:79], v[78:79], v[78:79], v[80:81]
	v_mov_b32_e32 v76, v57
	v_mov_b32_e32 v77, v61
	v_pk_fma_f32 v[74:75], v[74:75], v[74:75], v[78:79]
	s_nop 0
	v_pk_fma_f32 v[72:73], v[76:77], v[76:77], v[74:75]
	s_nop 0
	v_add_f32_e32 v53, v72, v73
	v_mov_b32_e32 v80, v63
	v_mov_b32_e32 v81, v67
	v_mov_b32_e32 v78, v62
	v_mov_b32_e32 v79, v66
	v_pk_mul_f32 v[80:81], v[80:81], v[80:81]
	v_mov_b32_e32 v74, v64
	v_mov_b32_e32 v75, v68
	v_pk_fma_f32 v[78:79], v[78:79], v[78:79], v[80:81]
	v_mov_b32_e32 v76, v65
	v_mov_b32_e32 v77, v69
	v_pk_fma_f32 v[74:75], v[74:75], v[74:75], v[78:79]
	s_nop 0
	v_pk_fma_f32 v[74:75], v[76:77], v[76:77], v[74:75]
	s_nop 0
	v_add_f32_e32 v53, v53, v74
	v_add_f32_e32 v53, v53, v75
	ds_bpermute_b32 v72, v44, v53
	s_waitcnt lgkmcnt(0)
	v_add_f32_e32 v53, v53, v72
	ds_bpermute_b32 v72, v45, v53
	s_waitcnt lgkmcnt(0)
	v_add_f32_e32 v53, v53, v72
	ds_bpermute_b32 v72, v46, v53
	s_waitcnt lgkmcnt(0)
	v_add_f32_e32 v53, v53, v72
	ds_bpermute_b32 v72, v47, v53
	s_waitcnt lgkmcnt(0)
	v_add_f32_e32 v53, v53, v72
	ds_bpermute_b32 v72, v48, v53
	s_waitcnt lgkmcnt(0)
	v_add_f32_e32 v53, v53, v72
	ds_bpermute_b32 v72, v49, v53
	s_waitcnt lgkmcnt(0)
	v_add_f32_e32 v53, v53, v72
	v_fmamk_f32 v53, v53, 0x3a800000, v149
	v_cmp_gt_f32_e32 vcc, s26, v53
	v_mul_f32_e32 v72, 0x4b800000, v53
	s_nop 0
	v_cndmask_b32_e32 v53, v53, v72, vcc
	v_rsq_f32_e32 v53, v53
	s_nop 0
	v_mul_f32_e32 v72, 0x45800000, v53
	v_cndmask_b32_e32 v72, v53, v72, vcc
	v_pk_mul_f32 v[54:55], v[72:73], v[54:55] op_sel_hi:[0,1]
	v_pk_mul_f32 v[56:57], v[72:73], v[56:57] op_sel_hi:[0,1]
	v_pk_fma_f32 v[54:55], v[54:55], v[28:29], v[2:3]
	v_pk_fma_f32 v[56:57], v[56:57], v[30:31], v[4:5]
	v_cvt_pk_bf16_f32 v54, v54, v55
	v_cvt_pk_bf16_f32 v55, v56, v57
	global_store_dwordx2 v[70:71], v[54:55], off offset:-1024
	v_pk_mul_f32 v[54:55], v[72:73], v[58:59] op_sel_hi:[0,1]
	v_pk_mul_f32 v[56:57], v[72:73], v[60:61] op_sel_hi:[0,1]
	v_pk_fma_f32 v[54:55], v[54:55], v[32:33], v[6:7]
	v_pk_fma_f32 v[56:57], v[56:57], v[34:35], v[8:9]
	v_cvt_pk_bf16_f32 v54, v54, v55
	v_cvt_pk_bf16_f32 v55, v56, v57
	global_store_dwordx2 v[70:71], v[54:55], off offset:-512
	v_pk_mul_f32 v[54:55], v[72:73], v[62:63] op_sel_hi:[0,1]
	v_pk_mul_f32 v[56:57], v[72:73], v[64:65] op_sel_hi:[0,1]
	v_pk_fma_f32 v[54:55], v[54:55], v[36:37], v[10:11]
	v_pk_fma_f32 v[56:57], v[56:57], v[38:39], v[12:13]
	v_cvt_pk_bf16_f32 v54, v54, v55
	v_cvt_pk_bf16_f32 v55, v56, v57
	global_store_dwordx2 v[70:71], v[54:55], off
	v_pk_mul_f32 v[54:55], v[72:73], v[66:67] op_sel_hi:[0,1]
	v_pk_mul_f32 v[56:57], v[72:73], v[68:69] op_sel_hi:[0,1]
	v_pk_fma_f32 v[54:55], v[54:55], v[40:41], v[14:15]
	v_pk_fma_f32 v[56:57], v[56:57], v[42:43], v[16:17]
	v_cvt_pk_bf16_f32 v54, v54, v55
	v_cvt_pk_bf16_f32 v55, v56, v57
	global_store_dwordx2 v[70:71], v[54:55], off offset:512
	s_add_u32 s6, s6, 0x800
	s_addc_u32 s7, s7, 0
	v_lshl_add_u64 v[24:25], v[24:25], 0, s[48:49]
	global_load_dwordx4 v[54:57], v[24:25], off offset:-2048
	global_load_dwordx4 v[58:61], v[24:25], off offset:-1024
	global_load_dwordx4 v[62:65], v[24:25], off
	global_load_dwordx4 v[66:69], v[24:25], off offset:1024
	v_lshl_add_u64 v[70:71], v[26:27], 0, s[6:7]
	s_waitcnt vmcnt(16)
	v_mov_b32_e32 v80, v83
	v_mov_b32_e32 v81, v87
	v_mov_b32_e32 v78, v82
	v_mov_b32_e32 v79, v86
	v_pk_mul_f32 v[80:81], v[80:81], v[80:81]
	v_mov_b32_e32 v74, v84
	v_mov_b32_e32 v75, v88
	v_pk_fma_f32 v[78:79], v[78:79], v[78:79], v[80:81]
	v_mov_b32_e32 v76, v85
	v_mov_b32_e32 v77, v89
	v_pk_fma_f32 v[74:75], v[74:75], v[74:75], v[78:79]
	s_nop 0
	v_pk_fma_f32 v[72:73], v[76:77], v[76:77], v[74:75]
	s_nop 0
	v_add_f32_e32 v53, v72, v73
	v_mov_b32_e32 v80, v91
	v_mov_b32_e32 v81, v95
	v_mov_b32_e32 v78, v90
	v_mov_b32_e32 v79, v94
	v_pk_mul_f32 v[80:81], v[80:81], v[80:81]
	v_mov_b32_e32 v74, v92
	v_mov_b32_e32 v75, v96
	v_pk_fma_f32 v[78:79], v[78:79], v[78:79], v[80:81]
	v_mov_b32_e32 v76, v93
	v_mov_b32_e32 v77, v97
	v_pk_fma_f32 v[74:75], v[74:75], v[74:75], v[78:79]
	s_nop 0
	v_pk_fma_f32 v[74:75], v[76:77], v[76:77], v[74:75]
	s_nop 0
	v_add_f32_e32 v53, v53, v74
	v_add_f32_e32 v53, v53, v75
	ds_bpermute_b32 v72, v44, v53
	s_waitcnt lgkmcnt(0)
	v_add_f32_e32 v53, v53, v72
	ds_bpermute_b32 v72, v45, v53
	s_waitcnt lgkmcnt(0)
	v_add_f32_e32 v53, v53, v72
	ds_bpermute_b32 v72, v46, v53
	s_waitcnt lgkmcnt(0)
	v_add_f32_e32 v53, v53, v72
	ds_bpermute_b32 v72, v47, v53
	s_waitcnt lgkmcnt(0)
	v_add_f32_e32 v53, v53, v72
	ds_bpermute_b32 v72, v48, v53
	s_waitcnt lgkmcnt(0)
	v_add_f32_e32 v53, v53, v72
	ds_bpermute_b32 v72, v49, v53
	s_waitcnt lgkmcnt(0)
	v_add_f32_e32 v53, v53, v72
	v_fmamk_f32 v53, v53, 0x3a800000, v149
	v_cmp_gt_f32_e32 vcc, s26, v53
	v_mul_f32_e32 v72, 0x4b800000, v53
	s_nop 0
	v_cndmask_b32_e32 v53, v53, v72, vcc
	v_rsq_f32_e32 v53, v53
	s_nop 0
	v_mul_f32_e32 v72, 0x45800000, v53
	v_cndmask_b32_e32 v72, v53, v72, vcc
	v_pk_mul_f32 v[82:83], v[72:73], v[82:83] op_sel_hi:[0,1]
	v_pk_mul_f32 v[84:85], v[72:73], v[84:85] op_sel_hi:[0,1]
	v_pk_fma_f32 v[82:83], v[82:83], v[28:29], v[2:3]
	v_pk_fma_f32 v[84:85], v[84:85], v[30:31], v[4:5]
	v_cvt_pk_bf16_f32 v82, v82, v83
	v_cvt_pk_bf16_f32 v83, v84, v85
	global_store_dwordx2 v[70:71], v[82:83], off offset:-1024
	v_pk_mul_f32 v[82:83], v[72:73], v[86:87] op_sel_hi:[0,1]
	v_pk_mul_f32 v[84:85], v[72:73], v[88:89] op_sel_hi:[0,1]
	v_pk_fma_f32 v[82:83], v[82:83], v[32:33], v[6:7]
	v_pk_fma_f32 v[84:85], v[84:85], v[34:35], v[8:9]
	v_cvt_pk_bf16_f32 v82, v82, v83
	v_cvt_pk_bf16_f32 v83, v84, v85
	global_store_dwordx2 v[70:71], v[82:83], off offset:-512
	v_pk_mul_f32 v[82:83], v[72:73], v[90:91] op_sel_hi:[0,1]
	v_pk_mul_f32 v[84:85], v[72:73], v[92:93] op_sel_hi:[0,1]
	v_pk_fma_f32 v[82:83], v[82:83], v[36:37], v[10:11]
	v_pk_fma_f32 v[84:85], v[84:85], v[38:39], v[12:13]
	v_cvt_pk_bf16_f32 v82, v82, v83
	v_cvt_pk_bf16_f32 v83, v84, v85
	global_store_dwordx2 v[70:71], v[82:83], off
	v_pk_mul_f32 v[82:83], v[72:73], v[94:95] op_sel_hi:[0,1]
	v_pk_mul_f32 v[84:85], v[72:73], v[96:97] op_sel_hi:[0,1]
	v_pk_fma_f32 v[82:83], v[82:83], v[40:41], v[14:15]
	v_pk_fma_f32 v[84:85], v[84:85], v[42:43], v[16:17]
	v_cvt_pk_bf16_f32 v82, v82, v83
	v_cvt_pk_bf16_f32 v83, v84, v85
	global_store_dwordx2 v[70:71], v[82:83], off offset:512
	s_add_u32 s6, s6, 0x800
	s_addc_u32 s7, s7, 0
	v_lshl_add_u64 v[24:25], v[24:25], 0, s[48:49]
	global_load_dwordx4 v[82:85], v[24:25], off offset:-2048
	global_load_dwordx4 v[86:89], v[24:25], off offset:-1024
	global_load_dwordx4 v[90:93], v[24:25], off
	global_load_dwordx4 v[94:97], v[24:25], off offset:1024
	v_lshl_add_u64 v[70:71], v[26:27], 0, s[6:7]
	s_waitcnt vmcnt(20)
	v_mov_b32_e32 v80, v99
	v_mov_b32_e32 v81, v103
	v_mov_b32_e32 v78, v98
	v_mov_b32_e32 v79, v102
	v_pk_mul_f32 v[80:81], v[80:81], v[80:81]
	v_mov_b32_e32 v74, v100
	v_mov_b32_e32 v75, v104
	v_pk_fma_f32 v[78:79], v[78:79], v[78:79], v[80:81]
	v_mov_b32_e32 v76, v101
	v_mov_b32_e32 v77, v105
	v_pk_fma_f32 v[74:75], v[74:75], v[74:75], v[78:79]
	s_nop 0
	v_pk_fma_f32 v[72:73], v[76:77], v[76:77], v[74:75]
	s_nop 0
	v_add_f32_e32 v53, v72, v73
	v_mov_b32_e32 v80, v107
	v_mov_b32_e32 v81, v111
	v_mov_b32_e32 v78, v106
	v_mov_b32_e32 v79, v110
	v_pk_mul_f32 v[80:81], v[80:81], v[80:81]
	v_mov_b32_e32 v74, v108
	v_mov_b32_e32 v75, v112
	v_pk_fma_f32 v[78:79], v[78:79], v[78:79], v[80:81]
	v_mov_b32_e32 v76, v109
	v_mov_b32_e32 v77, v113
	v_pk_fma_f32 v[74:75], v[74:75], v[74:75], v[78:79]
	s_nop 0
	v_pk_fma_f32 v[74:75], v[76:77], v[76:77], v[74:75]
	s_nop 0
	v_add_f32_e32 v53, v53, v74
	v_add_f32_e32 v53, v53, v75
	ds_bpermute_b32 v72, v44, v53
	s_waitcnt lgkmcnt(0)
	v_add_f32_e32 v53, v53, v72
	ds_bpermute_b32 v72, v45, v53
	s_waitcnt lgkmcnt(0)
	v_add_f32_e32 v53, v53, v72
	ds_bpermute_b32 v72, v46, v53
	s_waitcnt lgkmcnt(0)
	v_add_f32_e32 v53, v53, v72
	ds_bpermute_b32 v72, v47, v53
	s_waitcnt lgkmcnt(0)
	v_add_f32_e32 v53, v53, v72
	ds_bpermute_b32 v72, v48, v53
	s_waitcnt lgkmcnt(0)
	v_add_f32_e32 v53, v53, v72
	ds_bpermute_b32 v72, v49, v53
	s_waitcnt lgkmcnt(0)
	v_add_f32_e32 v53, v53, v72
	v_fmamk_f32 v53, v53, 0x3a800000, v149
	v_cmp_gt_f32_e32 vcc, s26, v53
	v_mul_f32_e32 v72, 0x4b800000, v53
	s_nop 0
	v_cndmask_b32_e32 v53, v53, v72, vcc
	v_rsq_f32_e32 v53, v53
	s_nop 0
	v_mul_f32_e32 v72, 0x45800000, v53
	v_cndmask_b32_e32 v72, v53, v72, vcc
	v_pk_mul_f32 v[98:99], v[72:73], v[98:99] op_sel_hi:[0,1]
	v_pk_mul_f32 v[100:101], v[72:73], v[100:101] op_sel_hi:[0,1]
	v_pk_fma_f32 v[98:99], v[98:99], v[28:29], v[2:3]
	v_pk_fma_f32 v[100:101], v[100:101], v[30:31], v[4:5]
	v_cvt_pk_bf16_f32 v98, v98, v99
	v_cvt_pk_bf16_f32 v99, v100, v101
	global_store_dwordx2 v[70:71], v[98:99], off offset:-1024
	v_pk_mul_f32 v[98:99], v[72:73], v[102:103] op_sel_hi:[0,1]
	v_pk_mul_f32 v[100:101], v[72:73], v[104:105] op_sel_hi:[0,1]
	v_pk_fma_f32 v[98:99], v[98:99], v[32:33], v[6:7]
	v_pk_fma_f32 v[100:101], v[100:101], v[34:35], v[8:9]
	v_cvt_pk_bf16_f32 v98, v98, v99
	v_cvt_pk_bf16_f32 v99, v100, v101
	global_store_dwordx2 v[70:71], v[98:99], off offset:-512
	v_pk_mul_f32 v[98:99], v[72:73], v[106:107] op_sel_hi:[0,1]
	v_pk_mul_f32 v[100:101], v[72:73], v[108:109] op_sel_hi:[0,1]
	v_pk_fma_f32 v[98:99], v[98:99], v[36:37], v[10:11]
	v_pk_fma_f32 v[100:101], v[100:101], v[38:39], v[12:13]
	v_cvt_pk_bf16_f32 v98, v98, v99
	v_cvt_pk_bf16_f32 v99, v100, v101
	global_store_dwordx2 v[70:71], v[98:99], off
	v_pk_mul_f32 v[98:99], v[72:73], v[110:111] op_sel_hi:[0,1]
	v_pk_mul_f32 v[100:101], v[72:73], v[112:113] op_sel_hi:[0,1]
	v_pk_fma_f32 v[98:99], v[98:99], v[40:41], v[14:15]
	v_pk_fma_f32 v[100:101], v[100:101], v[42:43], v[16:17]
	v_cvt_pk_bf16_f32 v98, v98, v99
	v_cvt_pk_bf16_f32 v99, v100, v101
	global_store_dwordx2 v[70:71], v[98:99], off offset:512
	s_add_u32 s6, s6, 0x800
	s_addc_u32 s7, s7, 0
	v_lshl_add_u64 v[24:25], v[24:25], 0, s[48:49]
	global_load_dwordx4 v[98:101], v[24:25], off offset:-2048
	global_load_dwordx4 v[102:105], v[24:25], off offset:-1024
	global_load_dwordx4 v[106:109], v[24:25], off
	global_load_dwordx4 v[110:113], v[24:25], off offset:1024
	v_lshl_add_u64 v[70:71], v[26:27], 0, s[6:7]
	s_waitcnt vmcnt(24)
	v_mov_b32_e32 v80, v115
	v_mov_b32_e32 v81, v119
	v_mov_b32_e32 v78, v114
	v_mov_b32_e32 v79, v118
	v_pk_mul_f32 v[80:81], v[80:81], v[80:81]
	v_mov_b32_e32 v74, v116
	v_mov_b32_e32 v75, v120
	v_pk_fma_f32 v[78:79], v[78:79], v[78:79], v[80:81]
	v_mov_b32_e32 v76, v117
	v_mov_b32_e32 v77, v121
	v_pk_fma_f32 v[74:75], v[74:75], v[74:75], v[78:79]
	s_nop 0
	v_pk_fma_f32 v[72:73], v[76:77], v[76:77], v[74:75]
	s_nop 0
	v_add_f32_e32 v53, v72, v73
	v_mov_b32_e32 v80, v123
	v_mov_b32_e32 v81, v127
	v_mov_b32_e32 v78, v122
	v_mov_b32_e32 v79, v126
	v_pk_mul_f32 v[80:81], v[80:81], v[80:81]
	v_mov_b32_e32 v74, v124
	v_mov_b32_e32 v75, v128
	v_pk_fma_f32 v[78:79], v[78:79], v[78:79], v[80:81]
	v_mov_b32_e32 v76, v125
	v_mov_b32_e32 v77, v129
	v_pk_fma_f32 v[74:75], v[74:75], v[74:75], v[78:79]
	s_nop 0
	v_pk_fma_f32 v[74:75], v[76:77], v[76:77], v[74:75]
	s_nop 0
	v_add_f32_e32 v53, v53, v74
	v_add_f32_e32 v53, v53, v75
	ds_bpermute_b32 v72, v44, v53
	s_waitcnt lgkmcnt(0)
	v_add_f32_e32 v53, v53, v72
	ds_bpermute_b32 v72, v45, v53
	s_waitcnt lgkmcnt(0)
	v_add_f32_e32 v53, v53, v72
	ds_bpermute_b32 v72, v46, v53
	s_waitcnt lgkmcnt(0)
	v_add_f32_e32 v53, v53, v72
	ds_bpermute_b32 v72, v47, v53
	s_waitcnt lgkmcnt(0)
	v_add_f32_e32 v53, v53, v72
	ds_bpermute_b32 v72, v48, v53
	s_waitcnt lgkmcnt(0)
	v_add_f32_e32 v53, v53, v72
	ds_bpermute_b32 v72, v49, v53
	s_waitcnt lgkmcnt(0)
	v_add_f32_e32 v53, v53, v72
	v_fmamk_f32 v53, v53, 0x3a800000, v149
	v_cmp_gt_f32_e32 vcc, s26, v53
	v_mul_f32_e32 v72, 0x4b800000, v53
	s_nop 0
	v_cndmask_b32_e32 v53, v53, v72, vcc
	v_rsq_f32_e32 v53, v53
	s_nop 0
	v_mul_f32_e32 v72, 0x45800000, v53
	v_cndmask_b32_e32 v72, v53, v72, vcc
	v_pk_mul_f32 v[114:115], v[72:73], v[114:115] op_sel_hi:[0,1]
	v_pk_mul_f32 v[116:117], v[72:73], v[116:117] op_sel_hi:[0,1]
	v_pk_fma_f32 v[114:115], v[114:115], v[28:29], v[2:3]
	v_pk_fma_f32 v[116:117], v[116:117], v[30:31], v[4:5]
	v_cvt_pk_bf16_f32 v114, v114, v115
	v_cvt_pk_bf16_f32 v115, v116, v117
	global_store_dwordx2 v[70:71], v[114:115], off offset:-1024
	v_pk_mul_f32 v[114:115], v[72:73], v[118:119] op_sel_hi:[0,1]
	v_pk_mul_f32 v[116:117], v[72:73], v[120:121] op_sel_hi:[0,1]
	v_pk_fma_f32 v[114:115], v[114:115], v[32:33], v[6:7]
	v_pk_fma_f32 v[116:117], v[116:117], v[34:35], v[8:9]
	v_cvt_pk_bf16_f32 v114, v114, v115
	v_cvt_pk_bf16_f32 v115, v116, v117
	global_store_dwordx2 v[70:71], v[114:115], off offset:-512
	v_pk_mul_f32 v[114:115], v[72:73], v[122:123] op_sel_hi:[0,1]
	v_pk_mul_f32 v[116:117], v[72:73], v[124:125] op_sel_hi:[0,1]
	v_pk_fma_f32 v[114:115], v[114:115], v[36:37], v[10:11]
	v_pk_fma_f32 v[116:117], v[116:117], v[38:39], v[12:13]
	v_cvt_pk_bf16_f32 v114, v114, v115
	v_cvt_pk_bf16_f32 v115, v116, v117
	global_store_dwordx2 v[70:71], v[114:115], off
	v_pk_mul_f32 v[114:115], v[72:73], v[126:127] op_sel_hi:[0,1]
	v_pk_mul_f32 v[116:117], v[72:73], v[128:129] op_sel_hi:[0,1]
	v_pk_fma_f32 v[114:115], v[114:115], v[40:41], v[14:15]
	v_pk_fma_f32 v[116:117], v[116:117], v[42:43], v[16:17]
	v_cvt_pk_bf16_f32 v114, v114, v115
	v_cvt_pk_bf16_f32 v115, v116, v117
	global_store_dwordx2 v[70:71], v[114:115], off offset:512
	s_add_u32 s6, s6, 0x800
	s_addc_u32 s7, s7, 0
	v_lshl_add_u64 v[24:25], v[24:25], 0, s[48:49]
	global_load_dwordx4 v[114:117], v[24:25], off offset:-2048
	global_load_dwordx4 v[118:121], v[24:25], off offset:-1024
	global_load_dwordx4 v[122:125], v[24:25], off
	global_load_dwordx4 v[126:129], v[24:25], off offset:1024
	v_lshl_add_u64 v[70:71], v[26:27], 0, s[6:7]
	s_waitcnt vmcnt(24)
	v_mov_b32_e32 v80, v55
	v_mov_b32_e32 v81, v59
	v_mov_b32_e32 v78, v54
	v_mov_b32_e32 v79, v58
	v_pk_mul_f32 v[80:81], v[80:81], v[80:81]
	v_mov_b32_e32 v74, v56
	v_mov_b32_e32 v75, v60
	v_pk_fma_f32 v[78:79], v[78:79], v[78:79], v[80:81]
	v_mov_b32_e32 v76, v57
	v_mov_b32_e32 v77, v61
	v_pk_fma_f32 v[74:75], v[74:75], v[74:75], v[78:79]
	s_nop 0
	v_pk_fma_f32 v[72:73], v[76:77], v[76:77], v[74:75]
	s_nop 0
	v_add_f32_e32 v53, v72, v73
	v_mov_b32_e32 v80, v63
	v_mov_b32_e32 v81, v67
	v_mov_b32_e32 v78, v62
	v_mov_b32_e32 v79, v66
	v_pk_mul_f32 v[80:81], v[80:81], v[80:81]
	v_mov_b32_e32 v74, v64
	v_mov_b32_e32 v75, v68
	v_pk_fma_f32 v[78:79], v[78:79], v[78:79], v[80:81]
	v_mov_b32_e32 v76, v65
	v_mov_b32_e32 v77, v69
	v_pk_fma_f32 v[74:75], v[74:75], v[74:75], v[78:79]
	s_nop 0
	v_pk_fma_f32 v[74:75], v[76:77], v[76:77], v[74:75]
	s_nop 0
	v_add_f32_e32 v53, v53, v74
	v_add_f32_e32 v53, v53, v75
	ds_bpermute_b32 v72, v44, v53
	s_waitcnt lgkmcnt(0)
	v_add_f32_e32 v53, v53, v72
	ds_bpermute_b32 v72, v45, v53
	s_waitcnt lgkmcnt(0)
	v_add_f32_e32 v53, v53, v72
	ds_bpermute_b32 v72, v46, v53
	s_waitcnt lgkmcnt(0)
	v_add_f32_e32 v53, v53, v72
	ds_bpermute_b32 v72, v47, v53
	s_waitcnt lgkmcnt(0)
	v_add_f32_e32 v53, v53, v72
	ds_bpermute_b32 v72, v48, v53
	s_waitcnt lgkmcnt(0)
	v_add_f32_e32 v53, v53, v72
	ds_bpermute_b32 v72, v49, v53
	s_waitcnt lgkmcnt(0)
	v_add_f32_e32 v53, v53, v72
	v_fmamk_f32 v53, v53, 0x3a800000, v149
	v_cmp_gt_f32_e32 vcc, s26, v53
	v_mul_f32_e32 v72, 0x4b800000, v53
	s_nop 0
	v_cndmask_b32_e32 v53, v53, v72, vcc
	v_rsq_f32_e32 v53, v53
	s_nop 0
	v_mul_f32_e32 v72, 0x45800000, v53
	v_cndmask_b32_e32 v72, v53, v72, vcc
	v_pk_mul_f32 v[54:55], v[72:73], v[54:55] op_sel_hi:[0,1]
	v_pk_mul_f32 v[56:57], v[72:73], v[56:57] op_sel_hi:[0,1]
	v_pk_fma_f32 v[54:55], v[54:55], v[28:29], v[2:3]
	v_pk_fma_f32 v[56:57], v[56:57], v[30:31], v[4:5]
	v_cvt_pk_bf16_f32 v54, v54, v55
	v_cvt_pk_bf16_f32 v55, v56, v57
	global_store_dwordx2 v[70:71], v[54:55], off offset:-1024
	v_pk_mul_f32 v[54:55], v[72:73], v[58:59] op_sel_hi:[0,1]
	v_pk_mul_f32 v[56:57], v[72:73], v[60:61] op_sel_hi:[0,1]
	v_pk_fma_f32 v[54:55], v[54:55], v[32:33], v[6:7]
	v_pk_fma_f32 v[56:57], v[56:57], v[34:35], v[8:9]
	v_cvt_pk_bf16_f32 v54, v54, v55
	v_cvt_pk_bf16_f32 v55, v56, v57
	global_store_dwordx2 v[70:71], v[54:55], off offset:-512
	v_pk_mul_f32 v[54:55], v[72:73], v[62:63] op_sel_hi:[0,1]
	v_pk_mul_f32 v[56:57], v[72:73], v[64:65] op_sel_hi:[0,1]
	v_pk_fma_f32 v[54:55], v[54:55], v[36:37], v[10:11]
	v_pk_fma_f32 v[56:57], v[56:57], v[38:39], v[12:13]
	v_cvt_pk_bf16_f32 v54, v54, v55
	v_cvt_pk_bf16_f32 v55, v56, v57
	global_store_dwordx2 v[70:71], v[54:55], off
	v_pk_mul_f32 v[54:55], v[72:73], v[66:67] op_sel_hi:[0,1]
	v_pk_mul_f32 v[56:57], v[72:73], v[68:69] op_sel_hi:[0,1]
	v_pk_fma_f32 v[54:55], v[54:55], v[40:41], v[14:15]
	v_pk_fma_f32 v[56:57], v[56:57], v[42:43], v[16:17]
	v_cvt_pk_bf16_f32 v54, v54, v55
	v_cvt_pk_bf16_f32 v55, v56, v57
	global_store_dwordx2 v[70:71], v[54:55], off offset:512
	s_add_u32 s6, s6, 0x800
	s_addc_u32 s7, s7, 0
	v_lshl_add_u64 v[24:25], v[24:25], 0, s[48:49]
	global_load_dwordx4 v[54:57], v[24:25], off offset:-2048
	global_load_dwordx4 v[58:61], v[24:25], off offset:-1024
	global_load_dwordx4 v[62:65], v[24:25], off
	global_load_dwordx4 v[66:69], v[24:25], off offset:1024
	v_lshl_add_u64 v[70:71], v[26:27], 0, s[6:7]
	s_waitcnt vmcnt(24)
	v_mov_b32_e32 v80, v83
	v_mov_b32_e32 v81, v87
	v_mov_b32_e32 v78, v82
	v_mov_b32_e32 v79, v86
	v_pk_mul_f32 v[80:81], v[80:81], v[80:81]
	v_mov_b32_e32 v74, v84
	v_mov_b32_e32 v75, v88
	v_pk_fma_f32 v[78:79], v[78:79], v[78:79], v[80:81]
	v_mov_b32_e32 v76, v85
	v_mov_b32_e32 v77, v89
	v_pk_fma_f32 v[74:75], v[74:75], v[74:75], v[78:79]
	s_nop 0
	v_pk_fma_f32 v[72:73], v[76:77], v[76:77], v[74:75]
	s_nop 0
	v_add_f32_e32 v53, v72, v73
	v_mov_b32_e32 v80, v91
	v_mov_b32_e32 v81, v95
	v_mov_b32_e32 v78, v90
	v_mov_b32_e32 v79, v94
	v_pk_mul_f32 v[80:81], v[80:81], v[80:81]
	v_mov_b32_e32 v74, v92
	v_mov_b32_e32 v75, v96
	v_pk_fma_f32 v[78:79], v[78:79], v[78:79], v[80:81]
	v_mov_b32_e32 v76, v93
	v_mov_b32_e32 v77, v97
	v_pk_fma_f32 v[74:75], v[74:75], v[74:75], v[78:79]
	s_nop 0
	v_pk_fma_f32 v[74:75], v[76:77], v[76:77], v[74:75]
	s_nop 0
	v_add_f32_e32 v53, v53, v74
	v_add_f32_e32 v53, v53, v75
	ds_bpermute_b32 v72, v44, v53
	s_waitcnt lgkmcnt(0)
	v_add_f32_e32 v53, v53, v72
	ds_bpermute_b32 v72, v45, v53
	s_waitcnt lgkmcnt(0)
	v_add_f32_e32 v53, v53, v72
	ds_bpermute_b32 v72, v46, v53
	s_waitcnt lgkmcnt(0)
	v_add_f32_e32 v53, v53, v72
	ds_bpermute_b32 v72, v47, v53
	s_waitcnt lgkmcnt(0)
	v_add_f32_e32 v53, v53, v72
	ds_bpermute_b32 v72, v48, v53
	s_waitcnt lgkmcnt(0)
	v_add_f32_e32 v53, v53, v72
	ds_bpermute_b32 v72, v49, v53
	s_waitcnt lgkmcnt(0)
	v_add_f32_e32 v53, v53, v72
	v_fmamk_f32 v53, v53, 0x3a800000, v149
	v_cmp_gt_f32_e32 vcc, s26, v53
	v_mul_f32_e32 v72, 0x4b800000, v53
	s_nop 0
	v_cndmask_b32_e32 v53, v53, v72, vcc
	v_rsq_f32_e32 v53, v53
	s_nop 0
	v_mul_f32_e32 v72, 0x45800000, v53
	v_cndmask_b32_e32 v72, v53, v72, vcc
	v_pk_mul_f32 v[82:83], v[72:73], v[82:83] op_sel_hi:[0,1]
	v_pk_mul_f32 v[84:85], v[72:73], v[84:85] op_sel_hi:[0,1]
	v_pk_fma_f32 v[82:83], v[82:83], v[28:29], v[2:3]
	v_pk_fma_f32 v[84:85], v[84:85], v[30:31], v[4:5]
	v_cvt_pk_bf16_f32 v82, v82, v83
	v_cvt_pk_bf16_f32 v83, v84, v85
	global_store_dwordx2 v[70:71], v[82:83], off offset:-1024
	v_pk_mul_f32 v[82:83], v[72:73], v[86:87] op_sel_hi:[0,1]
	v_pk_mul_f32 v[84:85], v[72:73], v[88:89] op_sel_hi:[0,1]
	v_pk_fma_f32 v[82:83], v[82:83], v[32:33], v[6:7]
	v_pk_fma_f32 v[84:85], v[84:85], v[34:35], v[8:9]
	v_cvt_pk_bf16_f32 v82, v82, v83
	v_cvt_pk_bf16_f32 v83, v84, v85
	global_store_dwordx2 v[70:71], v[82:83], off offset:-512
	v_pk_mul_f32 v[82:83], v[72:73], v[90:91] op_sel_hi:[0,1]
	v_pk_mul_f32 v[84:85], v[72:73], v[92:93] op_sel_hi:[0,1]
	v_pk_fma_f32 v[82:83], v[82:83], v[36:37], v[10:11]
	v_pk_fma_f32 v[84:85], v[84:85], v[38:39], v[12:13]
	v_cvt_pk_bf16_f32 v82, v82, v83
	v_cvt_pk_bf16_f32 v83, v84, v85
	global_store_dwordx2 v[70:71], v[82:83], off
	v_pk_mul_f32 v[82:83], v[72:73], v[94:95] op_sel_hi:[0,1]
	v_pk_mul_f32 v[84:85], v[72:73], v[96:97] op_sel_hi:[0,1]
	v_pk_fma_f32 v[82:83], v[82:83], v[40:41], v[14:15]
	v_pk_fma_f32 v[84:85], v[84:85], v[42:43], v[16:17]
	v_cvt_pk_bf16_f32 v82, v82, v83
	v_cvt_pk_bf16_f32 v83, v84, v85
	global_store_dwordx2 v[70:71], v[82:83], off offset:512
	s_add_u32 s6, s6, 0x800
	s_addc_u32 s7, s7, 0
	v_lshl_add_u64 v[24:25], v[24:25], 0, s[48:49]
	global_load_dwordx4 v[82:85], v[24:25], off offset:-2048
	global_load_dwordx4 v[86:89], v[24:25], off offset:-1024
	global_load_dwordx4 v[90:93], v[24:25], off
	global_load_dwordx4 v[94:97], v[24:25], off offset:1024
	v_lshl_add_u64 v[70:71], v[26:27], 0, s[6:7]
	s_waitcnt vmcnt(24)
	v_mov_b32_e32 v80, v99
	v_mov_b32_e32 v81, v103
	v_mov_b32_e32 v78, v98
	v_mov_b32_e32 v79, v102
	v_pk_mul_f32 v[80:81], v[80:81], v[80:81]
	v_mov_b32_e32 v74, v100
	v_mov_b32_e32 v75, v104
	v_pk_fma_f32 v[78:79], v[78:79], v[78:79], v[80:81]
	v_mov_b32_e32 v76, v101
	v_mov_b32_e32 v77, v105
	v_pk_fma_f32 v[74:75], v[74:75], v[74:75], v[78:79]
	s_nop 0
	v_pk_fma_f32 v[72:73], v[76:77], v[76:77], v[74:75]
	s_nop 0
	v_add_f32_e32 v53, v72, v73
	v_mov_b32_e32 v80, v107
	v_mov_b32_e32 v81, v111
	v_mov_b32_e32 v78, v106
	v_mov_b32_e32 v79, v110
	v_pk_mul_f32 v[80:81], v[80:81], v[80:81]
	v_mov_b32_e32 v74, v108
	v_mov_b32_e32 v75, v112
	v_pk_fma_f32 v[78:79], v[78:79], v[78:79], v[80:81]
	v_mov_b32_e32 v76, v109
	v_mov_b32_e32 v77, v113
	v_pk_fma_f32 v[74:75], v[74:75], v[74:75], v[78:79]
	s_nop 0
	v_pk_fma_f32 v[74:75], v[76:77], v[76:77], v[74:75]
	s_nop 0
	v_add_f32_e32 v53, v53, v74
	v_add_f32_e32 v53, v53, v75
	ds_bpermute_b32 v72, v44, v53
	s_waitcnt lgkmcnt(0)
	v_add_f32_e32 v53, v53, v72
	ds_bpermute_b32 v72, v45, v53
	s_waitcnt lgkmcnt(0)
	v_add_f32_e32 v53, v53, v72
	ds_bpermute_b32 v72, v46, v53
	s_waitcnt lgkmcnt(0)
	v_add_f32_e32 v53, v53, v72
	ds_bpermute_b32 v72, v47, v53
	s_waitcnt lgkmcnt(0)
	v_add_f32_e32 v53, v53, v72
	ds_bpermute_b32 v72, v48, v53
	s_waitcnt lgkmcnt(0)
	v_add_f32_e32 v53, v53, v72
	ds_bpermute_b32 v72, v49, v53
	s_waitcnt lgkmcnt(0)
	v_add_f32_e32 v53, v53, v72
	v_fmamk_f32 v53, v53, 0x3a800000, v149
	v_cmp_gt_f32_e32 vcc, s26, v53
	v_mul_f32_e32 v72, 0x4b800000, v53
	s_nop 0
	v_cndmask_b32_e32 v53, v53, v72, vcc
	v_rsq_f32_e32 v53, v53
	s_nop 0
	v_mul_f32_e32 v72, 0x45800000, v53
	v_cndmask_b32_e32 v72, v53, v72, vcc
	v_pk_mul_f32 v[98:99], v[72:73], v[98:99] op_sel_hi:[0,1]
	v_pk_mul_f32 v[100:101], v[72:73], v[100:101] op_sel_hi:[0,1]
	v_pk_fma_f32 v[98:99], v[98:99], v[28:29], v[2:3]
	v_pk_fma_f32 v[100:101], v[100:101], v[30:31], v[4:5]
	v_cvt_pk_bf16_f32 v98, v98, v99
	v_cvt_pk_bf16_f32 v99, v100, v101
	global_store_dwordx2 v[70:71], v[98:99], off offset:-1024
	v_pk_mul_f32 v[98:99], v[72:73], v[102:103] op_sel_hi:[0,1]
	v_pk_mul_f32 v[100:101], v[72:73], v[104:105] op_sel_hi:[0,1]
	v_pk_fma_f32 v[98:99], v[98:99], v[32:33], v[6:7]
	v_pk_fma_f32 v[100:101], v[100:101], v[34:35], v[8:9]
	v_cvt_pk_bf16_f32 v98, v98, v99
	v_cvt_pk_bf16_f32 v99, v100, v101
	global_store_dwordx2 v[70:71], v[98:99], off offset:-512
	v_pk_mul_f32 v[98:99], v[72:73], v[106:107] op_sel_hi:[0,1]
	v_pk_mul_f32 v[100:101], v[72:73], v[108:109] op_sel_hi:[0,1]
	v_pk_fma_f32 v[98:99], v[98:99], v[36:37], v[10:11]
	v_pk_fma_f32 v[100:101], v[100:101], v[38:39], v[12:13]
	v_cvt_pk_bf16_f32 v98, v98, v99
	v_cvt_pk_bf16_f32 v99, v100, v101
	global_store_dwordx2 v[70:71], v[98:99], off
	v_pk_mul_f32 v[98:99], v[72:73], v[110:111] op_sel_hi:[0,1]
	v_pk_mul_f32 v[100:101], v[72:73], v[112:113] op_sel_hi:[0,1]
	v_pk_fma_f32 v[98:99], v[98:99], v[40:41], v[14:15]
	v_pk_fma_f32 v[100:101], v[100:101], v[42:43], v[16:17]
	v_cvt_pk_bf16_f32 v98, v98, v99
	v_cvt_pk_bf16_f32 v99, v100, v101
	global_store_dwordx2 v[70:71], v[98:99], off offset:512
	s_add_u32 s6, s6, 0x800
	s_addc_u32 s7, s7, 0
	v_lshl_add_u64 v[24:25], v[24:25], 0, s[48:49]
	global_load_dwordx4 v[98:101], v[24:25], off offset:-2048
	global_load_dwordx4 v[102:105], v[24:25], off offset:-1024
	global_load_dwordx4 v[106:109], v[24:25], off
	global_load_dwordx4 v[110:113], v[24:25], off offset:1024
	v_lshl_add_u64 v[70:71], v[26:27], 0, s[6:7]
	s_waitcnt vmcnt(24)
	v_mov_b32_e32 v80, v115
	v_mov_b32_e32 v81, v119
	v_mov_b32_e32 v78, v114
	v_mov_b32_e32 v79, v118
	v_pk_mul_f32 v[80:81], v[80:81], v[80:81]
	v_mov_b32_e32 v74, v116
	v_mov_b32_e32 v75, v120
	v_pk_fma_f32 v[78:79], v[78:79], v[78:79], v[80:81]
	v_mov_b32_e32 v76, v117
	v_mov_b32_e32 v77, v121
	v_pk_fma_f32 v[74:75], v[74:75], v[74:75], v[78:79]
	s_nop 0
	v_pk_fma_f32 v[72:73], v[76:77], v[76:77], v[74:75]
	s_nop 0
	v_add_f32_e32 v53, v72, v73
	v_mov_b32_e32 v80, v123
	v_mov_b32_e32 v81, v127
	v_mov_b32_e32 v78, v122
	v_mov_b32_e32 v79, v126
	v_pk_mul_f32 v[80:81], v[80:81], v[80:81]
	v_mov_b32_e32 v74, v124
	v_mov_b32_e32 v75, v128
	v_pk_fma_f32 v[78:79], v[78:79], v[78:79], v[80:81]
	v_mov_b32_e32 v76, v125
	v_mov_b32_e32 v77, v129
	v_pk_fma_f32 v[74:75], v[74:75], v[74:75], v[78:79]
	s_nop 0
	v_pk_fma_f32 v[74:75], v[76:77], v[76:77], v[74:75]
	s_nop 0
	v_add_f32_e32 v53, v53, v74
	v_add_f32_e32 v53, v53, v75
	ds_bpermute_b32 v72, v44, v53
	s_waitcnt lgkmcnt(0)
	v_add_f32_e32 v53, v53, v72
	ds_bpermute_b32 v72, v45, v53
	s_waitcnt lgkmcnt(0)
	v_add_f32_e32 v53, v53, v72
	ds_bpermute_b32 v72, v46, v53
	s_waitcnt lgkmcnt(0)
	v_add_f32_e32 v53, v53, v72
	ds_bpermute_b32 v72, v47, v53
	s_waitcnt lgkmcnt(0)
	v_add_f32_e32 v53, v53, v72
	ds_bpermute_b32 v72, v48, v53
	s_waitcnt lgkmcnt(0)
	v_add_f32_e32 v53, v53, v72
	ds_bpermute_b32 v72, v49, v53
	s_waitcnt lgkmcnt(0)
	v_add_f32_e32 v53, v53, v72
	v_fmamk_f32 v53, v53, 0x3a800000, v149
	v_cmp_gt_f32_e32 vcc, s26, v53
	v_mul_f32_e32 v72, 0x4b800000, v53
	s_nop 0
	v_cndmask_b32_e32 v53, v53, v72, vcc
	v_rsq_f32_e32 v53, v53
	s_nop 0
	v_mul_f32_e32 v72, 0x45800000, v53
	v_cndmask_b32_e32 v72, v53, v72, vcc
	v_pk_mul_f32 v[114:115], v[72:73], v[114:115] op_sel_hi:[0,1]
	v_pk_mul_f32 v[116:117], v[72:73], v[116:117] op_sel_hi:[0,1]
	v_pk_fma_f32 v[114:115], v[114:115], v[28:29], v[2:3]
	v_pk_fma_f32 v[116:117], v[116:117], v[30:31], v[4:5]
	v_cvt_pk_bf16_f32 v114, v114, v115
	v_cvt_pk_bf16_f32 v115, v116, v117
	global_store_dwordx2 v[70:71], v[114:115], off offset:-1024
	v_pk_mul_f32 v[114:115], v[72:73], v[118:119] op_sel_hi:[0,1]
	v_pk_mul_f32 v[116:117], v[72:73], v[120:121] op_sel_hi:[0,1]
	v_pk_fma_f32 v[114:115], v[114:115], v[32:33], v[6:7]
	v_pk_fma_f32 v[116:117], v[116:117], v[34:35], v[8:9]
	v_cvt_pk_bf16_f32 v114, v114, v115
	v_cvt_pk_bf16_f32 v115, v116, v117
	global_store_dwordx2 v[70:71], v[114:115], off offset:-512
	v_pk_mul_f32 v[114:115], v[72:73], v[122:123] op_sel_hi:[0,1]
	v_pk_mul_f32 v[116:117], v[72:73], v[124:125] op_sel_hi:[0,1]
	v_pk_fma_f32 v[114:115], v[114:115], v[36:37], v[10:11]
	v_pk_fma_f32 v[116:117], v[116:117], v[38:39], v[12:13]
	v_cvt_pk_bf16_f32 v114, v114, v115
	v_cvt_pk_bf16_f32 v115, v116, v117
	global_store_dwordx2 v[70:71], v[114:115], off
	v_pk_mul_f32 v[114:115], v[72:73], v[126:127] op_sel_hi:[0,1]
	v_pk_mul_f32 v[116:117], v[72:73], v[128:129] op_sel_hi:[0,1]
	v_pk_fma_f32 v[114:115], v[114:115], v[40:41], v[14:15]
	v_pk_fma_f32 v[116:117], v[116:117], v[42:43], v[16:17]
	v_cvt_pk_bf16_f32 v114, v114, v115
	v_cvt_pk_bf16_f32 v115, v116, v117
	global_store_dwordx2 v[70:71], v[114:115], off offset:512
	s_add_u32 s6, s6, 0x800
	s_addc_u32 s7, s7, 0
	v_lshl_add_u64 v[24:25], v[24:25], 0, s[48:49]
	global_load_dwordx4 v[114:117], v[24:25], off offset:-2048
	global_load_dwordx4 v[118:121], v[24:25], off offset:-1024
	global_load_dwordx4 v[122:125], v[24:25], off
	global_load_dwordx4 v[126:129], v[24:25], off offset:1024
	v_lshl_add_u64 v[70:71], v[26:27], 0, s[6:7]
	s_waitcnt vmcnt(24)
	v_mov_b32_e32 v80, v55
	v_mov_b32_e32 v81, v59
	v_mov_b32_e32 v78, v54
	v_mov_b32_e32 v79, v58
	v_pk_mul_f32 v[80:81], v[80:81], v[80:81]
	v_mov_b32_e32 v74, v56
	v_mov_b32_e32 v75, v60
	v_pk_fma_f32 v[78:79], v[78:79], v[78:79], v[80:81]
	v_mov_b32_e32 v76, v57
	v_mov_b32_e32 v77, v61
	v_pk_fma_f32 v[74:75], v[74:75], v[74:75], v[78:79]
	s_nop 0
	v_pk_fma_f32 v[72:73], v[76:77], v[76:77], v[74:75]
	s_nop 0
	v_add_f32_e32 v53, v72, v73
	v_mov_b32_e32 v80, v63
	v_mov_b32_e32 v81, v67
	v_mov_b32_e32 v78, v62
	v_mov_b32_e32 v79, v66
	v_pk_mul_f32 v[80:81], v[80:81], v[80:81]
	v_mov_b32_e32 v74, v64
	v_mov_b32_e32 v75, v68
	v_pk_fma_f32 v[78:79], v[78:79], v[78:79], v[80:81]
	v_mov_b32_e32 v76, v65
	v_mov_b32_e32 v77, v69
	v_pk_fma_f32 v[74:75], v[74:75], v[74:75], v[78:79]
	s_nop 0
	v_pk_fma_f32 v[74:75], v[76:77], v[76:77], v[74:75]
	s_nop 0
	v_add_f32_e32 v53, v53, v74
	v_add_f32_e32 v53, v53, v75
	ds_bpermute_b32 v72, v44, v53
	s_waitcnt lgkmcnt(0)
	v_add_f32_e32 v53, v53, v72
	ds_bpermute_b32 v72, v45, v53
	s_waitcnt lgkmcnt(0)
	v_add_f32_e32 v53, v53, v72
	ds_bpermute_b32 v72, v46, v53
	s_waitcnt lgkmcnt(0)
	v_add_f32_e32 v53, v53, v72
	ds_bpermute_b32 v72, v47, v53
	s_waitcnt lgkmcnt(0)
	v_add_f32_e32 v53, v53, v72
	ds_bpermute_b32 v72, v48, v53
	s_waitcnt lgkmcnt(0)
	v_add_f32_e32 v53, v53, v72
	ds_bpermute_b32 v72, v49, v53
	s_waitcnt lgkmcnt(0)
	v_add_f32_e32 v53, v53, v72
	v_fmamk_f32 v53, v53, 0x3a800000, v149
	v_cmp_gt_f32_e32 vcc, s26, v53
	v_mul_f32_e32 v72, 0x4b800000, v53
	s_nop 0
	v_cndmask_b32_e32 v53, v53, v72, vcc
	v_rsq_f32_e32 v53, v53
	s_nop 0
	v_mul_f32_e32 v72, 0x45800000, v53
	v_cndmask_b32_e32 v72, v53, v72, vcc
	v_pk_mul_f32 v[54:55], v[72:73], v[54:55] op_sel_hi:[0,1]
	v_pk_mul_f32 v[56:57], v[72:73], v[56:57] op_sel_hi:[0,1]
	v_pk_fma_f32 v[54:55], v[54:55], v[28:29], v[2:3]
	v_pk_fma_f32 v[56:57], v[56:57], v[30:31], v[4:5]
	v_cvt_pk_bf16_f32 v54, v54, v55
	v_cvt_pk_bf16_f32 v55, v56, v57
	global_store_dwordx2 v[70:71], v[54:55], off offset:-1024
	v_pk_mul_f32 v[54:55], v[72:73], v[58:59] op_sel_hi:[0,1]
	v_pk_mul_f32 v[56:57], v[72:73], v[60:61] op_sel_hi:[0,1]
	v_pk_fma_f32 v[54:55], v[54:55], v[32:33], v[6:7]
	v_pk_fma_f32 v[56:57], v[56:57], v[34:35], v[8:9]
	v_cvt_pk_bf16_f32 v54, v54, v55
	v_cvt_pk_bf16_f32 v55, v56, v57
	global_store_dwordx2 v[70:71], v[54:55], off offset:-512
	v_pk_mul_f32 v[54:55], v[72:73], v[62:63] op_sel_hi:[0,1]
	v_pk_mul_f32 v[56:57], v[72:73], v[64:65] op_sel_hi:[0,1]
	v_pk_fma_f32 v[54:55], v[54:55], v[36:37], v[10:11]
	v_pk_fma_f32 v[56:57], v[56:57], v[38:39], v[12:13]
	v_cvt_pk_bf16_f32 v54, v54, v55
	v_cvt_pk_bf16_f32 v55, v56, v57
	global_store_dwordx2 v[70:71], v[54:55], off
	v_pk_mul_f32 v[54:55], v[72:73], v[66:67] op_sel_hi:[0,1]
	v_pk_mul_f32 v[56:57], v[72:73], v[68:69] op_sel_hi:[0,1]
	v_pk_fma_f32 v[54:55], v[54:55], v[40:41], v[14:15]
	v_pk_fma_f32 v[56:57], v[56:57], v[42:43], v[16:17]
	v_cvt_pk_bf16_f32 v54, v54, v55
	v_cvt_pk_bf16_f32 v55, v56, v57
	global_store_dwordx2 v[70:71], v[54:55], off offset:512
	s_add_u32 s6, s6, 0x800
	s_addc_u32 s7, s7, 0
	v_lshl_add_u64 v[24:25], v[24:25], 0, s[48:49]
	global_load_dwordx4 v[54:57], v[24:25], off offset:-2048
	global_load_dwordx4 v[58:61], v[24:25], off offset:-1024
	global_load_dwordx4 v[62:65], v[24:25], off
	global_load_dwordx4 v[66:69], v[24:25], off offset:1024
	v_lshl_add_u64 v[70:71], v[26:27], 0, s[6:7]
	s_waitcnt vmcnt(24)
	v_mov_b32_e32 v80, v83
	v_mov_b32_e32 v81, v87
	v_mov_b32_e32 v78, v82
	v_mov_b32_e32 v79, v86
	v_pk_mul_f32 v[80:81], v[80:81], v[80:81]
	v_mov_b32_e32 v74, v84
	v_mov_b32_e32 v75, v88
	v_pk_fma_f32 v[78:79], v[78:79], v[78:79], v[80:81]
	v_mov_b32_e32 v76, v85
	v_mov_b32_e32 v77, v89
	v_pk_fma_f32 v[74:75], v[74:75], v[74:75], v[78:79]
	s_nop 0
	v_pk_fma_f32 v[72:73], v[76:77], v[76:77], v[74:75]
	s_nop 0
	v_add_f32_e32 v53, v72, v73
	v_mov_b32_e32 v80, v91
	v_mov_b32_e32 v81, v95
	v_mov_b32_e32 v78, v90
	v_mov_b32_e32 v79, v94
	v_pk_mul_f32 v[80:81], v[80:81], v[80:81]
	v_mov_b32_e32 v74, v92
	v_mov_b32_e32 v75, v96
	v_pk_fma_f32 v[78:79], v[78:79], v[78:79], v[80:81]
	v_mov_b32_e32 v76, v93
	v_mov_b32_e32 v77, v97
	v_pk_fma_f32 v[74:75], v[74:75], v[74:75], v[78:79]
	s_nop 0
	v_pk_fma_f32 v[74:75], v[76:77], v[76:77], v[74:75]
	s_nop 0
	v_add_f32_e32 v53, v53, v74
	v_add_f32_e32 v53, v53, v75
	ds_bpermute_b32 v72, v44, v53
	s_waitcnt lgkmcnt(0)
	v_add_f32_e32 v53, v53, v72
	ds_bpermute_b32 v72, v45, v53
	s_waitcnt lgkmcnt(0)
	v_add_f32_e32 v53, v53, v72
	ds_bpermute_b32 v72, v46, v53
	s_waitcnt lgkmcnt(0)
	v_add_f32_e32 v53, v53, v72
	ds_bpermute_b32 v72, v47, v53
	s_waitcnt lgkmcnt(0)
	v_add_f32_e32 v53, v53, v72
	ds_bpermute_b32 v72, v48, v53
	s_waitcnt lgkmcnt(0)
	v_add_f32_e32 v53, v53, v72
	ds_bpermute_b32 v72, v49, v53
	s_waitcnt lgkmcnt(0)
	v_add_f32_e32 v53, v53, v72
	v_fmamk_f32 v53, v53, 0x3a800000, v149
	v_cmp_gt_f32_e32 vcc, s26, v53
	v_mul_f32_e32 v72, 0x4b800000, v53
	s_nop 0
	v_cndmask_b32_e32 v53, v53, v72, vcc
	v_rsq_f32_e32 v53, v53
	s_nop 0
	v_mul_f32_e32 v72, 0x45800000, v53
	v_cndmask_b32_e32 v72, v53, v72, vcc
	v_pk_mul_f32 v[82:83], v[72:73], v[82:83] op_sel_hi:[0,1]
	v_pk_mul_f32 v[84:85], v[72:73], v[84:85] op_sel_hi:[0,1]
	v_pk_fma_f32 v[82:83], v[82:83], v[28:29], v[2:3]
	v_pk_fma_f32 v[84:85], v[84:85], v[30:31], v[4:5]
	v_cvt_pk_bf16_f32 v82, v82, v83
	v_cvt_pk_bf16_f32 v83, v84, v85
	global_store_dwordx2 v[70:71], v[82:83], off offset:-1024
	v_pk_mul_f32 v[82:83], v[72:73], v[86:87] op_sel_hi:[0,1]
	v_pk_mul_f32 v[84:85], v[72:73], v[88:89] op_sel_hi:[0,1]
	v_pk_fma_f32 v[82:83], v[82:83], v[32:33], v[6:7]
	v_pk_fma_f32 v[84:85], v[84:85], v[34:35], v[8:9]
	v_cvt_pk_bf16_f32 v82, v82, v83
	v_cvt_pk_bf16_f32 v83, v84, v85
	global_store_dwordx2 v[70:71], v[82:83], off offset:-512
	v_pk_mul_f32 v[82:83], v[72:73], v[90:91] op_sel_hi:[0,1]
	v_pk_mul_f32 v[84:85], v[72:73], v[92:93] op_sel_hi:[0,1]
	v_pk_fma_f32 v[82:83], v[82:83], v[36:37], v[10:11]
	v_pk_fma_f32 v[84:85], v[84:85], v[38:39], v[12:13]
	v_cvt_pk_bf16_f32 v82, v82, v83
	v_cvt_pk_bf16_f32 v83, v84, v85
	global_store_dwordx2 v[70:71], v[82:83], off
	v_pk_mul_f32 v[82:83], v[72:73], v[94:95] op_sel_hi:[0,1]
	v_pk_mul_f32 v[84:85], v[72:73], v[96:97] op_sel_hi:[0,1]
	v_pk_fma_f32 v[82:83], v[82:83], v[40:41], v[14:15]
	v_pk_fma_f32 v[84:85], v[84:85], v[42:43], v[16:17]
	v_cvt_pk_bf16_f32 v82, v82, v83
	v_cvt_pk_bf16_f32 v83, v84, v85
	global_store_dwordx2 v[70:71], v[82:83], off offset:512
	s_add_u32 s6, s6, 0x800
	s_addc_u32 s7, s7, 0
	v_lshl_add_u64 v[24:25], v[24:25], 0, s[48:49]
	global_load_dwordx4 v[82:85], v[24:25], off offset:-2048
	global_load_dwordx4 v[86:89], v[24:25], off offset:-1024
	global_load_dwordx4 v[90:93], v[24:25], off
	global_load_dwordx4 v[94:97], v[24:25], off offset:1024
	v_lshl_add_u64 v[70:71], v[26:27], 0, s[6:7]
	s_waitcnt vmcnt(24)
	v_mov_b32_e32 v80, v99
	v_mov_b32_e32 v81, v103
	v_mov_b32_e32 v78, v98
	v_mov_b32_e32 v79, v102
	v_pk_mul_f32 v[80:81], v[80:81], v[80:81]
	v_mov_b32_e32 v74, v100
	v_mov_b32_e32 v75, v104
	v_pk_fma_f32 v[78:79], v[78:79], v[78:79], v[80:81]
	v_mov_b32_e32 v76, v101
	v_mov_b32_e32 v77, v105
	v_pk_fma_f32 v[74:75], v[74:75], v[74:75], v[78:79]
	s_nop 0
	v_pk_fma_f32 v[72:73], v[76:77], v[76:77], v[74:75]
	s_nop 0
	v_add_f32_e32 v53, v72, v73
	v_mov_b32_e32 v80, v107
	v_mov_b32_e32 v81, v111
	v_mov_b32_e32 v78, v106
	v_mov_b32_e32 v79, v110
	v_pk_mul_f32 v[80:81], v[80:81], v[80:81]
	v_mov_b32_e32 v74, v108
	v_mov_b32_e32 v75, v112
	v_pk_fma_f32 v[78:79], v[78:79], v[78:79], v[80:81]
	v_mov_b32_e32 v76, v109
	v_mov_b32_e32 v77, v113
	v_pk_fma_f32 v[74:75], v[74:75], v[74:75], v[78:79]
	s_nop 0
	v_pk_fma_f32 v[74:75], v[76:77], v[76:77], v[74:75]
	s_nop 0
	v_add_f32_e32 v53, v53, v74
	v_add_f32_e32 v53, v53, v75
	ds_bpermute_b32 v72, v44, v53
	s_waitcnt lgkmcnt(0)
	v_add_f32_e32 v53, v53, v72
	ds_bpermute_b32 v72, v45, v53
	s_waitcnt lgkmcnt(0)
	v_add_f32_e32 v53, v53, v72
	ds_bpermute_b32 v72, v46, v53
	s_waitcnt lgkmcnt(0)
	v_add_f32_e32 v53, v53, v72
	ds_bpermute_b32 v72, v47, v53
	s_waitcnt lgkmcnt(0)
	v_add_f32_e32 v53, v53, v72
	ds_bpermute_b32 v72, v48, v53
	s_waitcnt lgkmcnt(0)
	v_add_f32_e32 v53, v53, v72
	ds_bpermute_b32 v72, v49, v53
	s_waitcnt lgkmcnt(0)
	v_add_f32_e32 v53, v53, v72
	v_fmamk_f32 v53, v53, 0x3a800000, v149
	v_cmp_gt_f32_e32 vcc, s26, v53
	v_mul_f32_e32 v72, 0x4b800000, v53
	s_nop 0
	v_cndmask_b32_e32 v53, v53, v72, vcc
	v_rsq_f32_e32 v53, v53
	s_nop 0
	v_mul_f32_e32 v72, 0x45800000, v53
	v_cndmask_b32_e32 v72, v53, v72, vcc
	v_pk_mul_f32 v[98:99], v[72:73], v[98:99] op_sel_hi:[0,1]
	v_pk_mul_f32 v[100:101], v[72:73], v[100:101] op_sel_hi:[0,1]
	v_pk_fma_f32 v[98:99], v[98:99], v[28:29], v[2:3]
	v_pk_fma_f32 v[100:101], v[100:101], v[30:31], v[4:5]
	v_cvt_pk_bf16_f32 v98, v98, v99
	v_cvt_pk_bf16_f32 v99, v100, v101
	global_store_dwordx2 v[70:71], v[98:99], off offset:-1024
	v_pk_mul_f32 v[98:99], v[72:73], v[102:103] op_sel_hi:[0,1]
	v_pk_mul_f32 v[100:101], v[72:73], v[104:105] op_sel_hi:[0,1]
	v_pk_fma_f32 v[98:99], v[98:99], v[32:33], v[6:7]
	v_pk_fma_f32 v[100:101], v[100:101], v[34:35], v[8:9]
	v_cvt_pk_bf16_f32 v98, v98, v99
	v_cvt_pk_bf16_f32 v99, v100, v101
	global_store_dwordx2 v[70:71], v[98:99], off offset:-512
	v_pk_mul_f32 v[98:99], v[72:73], v[106:107] op_sel_hi:[0,1]
	v_pk_mul_f32 v[100:101], v[72:73], v[108:109] op_sel_hi:[0,1]
	v_pk_fma_f32 v[98:99], v[98:99], v[36:37], v[10:11]
	v_pk_fma_f32 v[100:101], v[100:101], v[38:39], v[12:13]
	v_cvt_pk_bf16_f32 v98, v98, v99
	v_cvt_pk_bf16_f32 v99, v100, v101
	global_store_dwordx2 v[70:71], v[98:99], off
	v_pk_mul_f32 v[98:99], v[72:73], v[110:111] op_sel_hi:[0,1]
	v_pk_mul_f32 v[100:101], v[72:73], v[112:113] op_sel_hi:[0,1]
	v_pk_fma_f32 v[98:99], v[98:99], v[40:41], v[14:15]
	v_pk_fma_f32 v[100:101], v[100:101], v[42:43], v[16:17]
	v_cvt_pk_bf16_f32 v98, v98, v99
	v_cvt_pk_bf16_f32 v99, v100, v101
	global_store_dwordx2 v[70:71], v[98:99], off offset:512
	s_add_u32 s6, s6, 0x800
	s_addc_u32 s7, s7, 0
	v_lshl_add_u64 v[24:25], v[24:25], 0, s[48:49]
	global_load_dwordx4 v[98:101], v[24:25], off offset:-2048
	global_load_dwordx4 v[102:105], v[24:25], off offset:-1024
	global_load_dwordx4 v[106:109], v[24:25], off
	global_load_dwordx4 v[110:113], v[24:25], off offset:1024
	v_lshl_add_u64 v[70:71], v[26:27], 0, s[6:7]
	s_waitcnt vmcnt(24)
	v_mov_b32_e32 v80, v115
	v_mov_b32_e32 v81, v119
	v_mov_b32_e32 v78, v114
	v_mov_b32_e32 v79, v118
	v_pk_mul_f32 v[80:81], v[80:81], v[80:81]
	v_mov_b32_e32 v74, v116
	v_mov_b32_e32 v75, v120
	v_pk_fma_f32 v[78:79], v[78:79], v[78:79], v[80:81]
	v_mov_b32_e32 v76, v117
	v_mov_b32_e32 v77, v121
	v_pk_fma_f32 v[74:75], v[74:75], v[74:75], v[78:79]
	s_nop 0
	v_pk_fma_f32 v[72:73], v[76:77], v[76:77], v[74:75]
	s_nop 0
	v_add_f32_e32 v53, v72, v73
	v_mov_b32_e32 v80, v123
	v_mov_b32_e32 v81, v127
	v_mov_b32_e32 v78, v122
	v_mov_b32_e32 v79, v126
	v_pk_mul_f32 v[80:81], v[80:81], v[80:81]
	v_mov_b32_e32 v74, v124
	v_mov_b32_e32 v75, v128
	v_pk_fma_f32 v[78:79], v[78:79], v[78:79], v[80:81]
	v_mov_b32_e32 v76, v125
	v_mov_b32_e32 v77, v129
	v_pk_fma_f32 v[74:75], v[74:75], v[74:75], v[78:79]
	s_nop 0
	v_pk_fma_f32 v[74:75], v[76:77], v[76:77], v[74:75]
	s_nop 0
	v_add_f32_e32 v53, v53, v74
	v_add_f32_e32 v53, v53, v75
	ds_bpermute_b32 v72, v44, v53
	s_waitcnt lgkmcnt(0)
	v_add_f32_e32 v53, v53, v72
	ds_bpermute_b32 v72, v45, v53
	s_waitcnt lgkmcnt(0)
	v_add_f32_e32 v53, v53, v72
	ds_bpermute_b32 v72, v46, v53
	s_waitcnt lgkmcnt(0)
	v_add_f32_e32 v53, v53, v72
	ds_bpermute_b32 v72, v47, v53
	s_waitcnt lgkmcnt(0)
	v_add_f32_e32 v53, v53, v72
	ds_bpermute_b32 v72, v48, v53
	s_waitcnt lgkmcnt(0)
	v_add_f32_e32 v53, v53, v72
	ds_bpermute_b32 v72, v49, v53
	s_waitcnt lgkmcnt(0)
	v_add_f32_e32 v53, v53, v72
	v_fmamk_f32 v53, v53, 0x3a800000, v149
	v_cmp_gt_f32_e32 vcc, s26, v53
	v_mul_f32_e32 v72, 0x4b800000, v53
	s_nop 0
	v_cndmask_b32_e32 v53, v53, v72, vcc
	v_rsq_f32_e32 v53, v53
	s_nop 0
	v_mul_f32_e32 v72, 0x45800000, v53
	v_cndmask_b32_e32 v72, v53, v72, vcc
	v_pk_mul_f32 v[114:115], v[72:73], v[114:115] op_sel_hi:[0,1]
	v_pk_mul_f32 v[116:117], v[72:73], v[116:117] op_sel_hi:[0,1]
	v_pk_fma_f32 v[114:115], v[114:115], v[28:29], v[2:3]
	v_pk_fma_f32 v[116:117], v[116:117], v[30:31], v[4:5]
	v_cvt_pk_bf16_f32 v114, v114, v115
	v_cvt_pk_bf16_f32 v115, v116, v117
	global_store_dwordx2 v[70:71], v[114:115], off offset:-1024
	v_pk_mul_f32 v[114:115], v[72:73], v[118:119] op_sel_hi:[0,1]
	v_pk_mul_f32 v[116:117], v[72:73], v[120:121] op_sel_hi:[0,1]
	v_pk_fma_f32 v[114:115], v[114:115], v[32:33], v[6:7]
	v_pk_fma_f32 v[116:117], v[116:117], v[34:35], v[8:9]
	v_cvt_pk_bf16_f32 v114, v114, v115
	v_cvt_pk_bf16_f32 v115, v116, v117
	global_store_dwordx2 v[70:71], v[114:115], off offset:-512
	v_pk_mul_f32 v[114:115], v[72:73], v[122:123] op_sel_hi:[0,1]
	v_pk_mul_f32 v[116:117], v[72:73], v[124:125] op_sel_hi:[0,1]
	v_pk_fma_f32 v[114:115], v[114:115], v[36:37], v[10:11]
	v_pk_fma_f32 v[116:117], v[116:117], v[38:39], v[12:13]
	v_cvt_pk_bf16_f32 v114, v114, v115
	v_cvt_pk_bf16_f32 v115, v116, v117
	global_store_dwordx2 v[70:71], v[114:115], off
	v_pk_mul_f32 v[114:115], v[72:73], v[126:127] op_sel_hi:[0,1]
	v_pk_mul_f32 v[116:117], v[72:73], v[128:129] op_sel_hi:[0,1]
	v_pk_fma_f32 v[114:115], v[114:115], v[40:41], v[14:15]
	v_pk_fma_f32 v[116:117], v[116:117], v[42:43], v[16:17]
	v_cvt_pk_bf16_f32 v114, v114, v115
	v_cvt_pk_bf16_f32 v115, v116, v117
	global_store_dwordx2 v[70:71], v[114:115], off offset:512
	s_add_u32 s6, s6, 0x800
	s_addc_u32 s7, s7, 0
	v_lshl_add_u64 v[24:25], v[24:25], 0, s[48:49]
	global_load_dwordx4 v[114:117], v[24:25], off offset:-2048
	global_load_dwordx4 v[118:121], v[24:25], off offset:-1024
	global_load_dwordx4 v[122:125], v[24:25], off
	global_load_dwordx4 v[126:129], v[24:25], off offset:1024
	v_lshl_add_u64 v[70:71], v[26:27], 0, s[6:7]
	s_waitcnt vmcnt(24)
	v_mov_b32_e32 v80, v55
	v_mov_b32_e32 v81, v59
	v_mov_b32_e32 v78, v54
	v_mov_b32_e32 v79, v58
	v_pk_mul_f32 v[80:81], v[80:81], v[80:81]
	v_mov_b32_e32 v74, v56
	v_mov_b32_e32 v75, v60
	v_pk_fma_f32 v[78:79], v[78:79], v[78:79], v[80:81]
	v_mov_b32_e32 v76, v57
	v_mov_b32_e32 v77, v61
	v_pk_fma_f32 v[74:75], v[74:75], v[74:75], v[78:79]
	s_nop 0
	v_pk_fma_f32 v[72:73], v[76:77], v[76:77], v[74:75]
	s_nop 0
	v_add_f32_e32 v53, v72, v73
	v_mov_b32_e32 v80, v63
	v_mov_b32_e32 v81, v67
	v_mov_b32_e32 v78, v62
	v_mov_b32_e32 v79, v66
	v_pk_mul_f32 v[80:81], v[80:81], v[80:81]
	v_mov_b32_e32 v74, v64
	v_mov_b32_e32 v75, v68
	v_pk_fma_f32 v[78:79], v[78:79], v[78:79], v[80:81]
	v_mov_b32_e32 v76, v65
	v_mov_b32_e32 v77, v69
	v_pk_fma_f32 v[74:75], v[74:75], v[74:75], v[78:79]
	s_nop 0
	v_pk_fma_f32 v[74:75], v[76:77], v[76:77], v[74:75]
	s_nop 0
	v_add_f32_e32 v53, v53, v74
	v_add_f32_e32 v53, v53, v75
	ds_bpermute_b32 v72, v44, v53
	s_waitcnt lgkmcnt(0)
	v_add_f32_e32 v53, v53, v72
	ds_bpermute_b32 v72, v45, v53
	s_waitcnt lgkmcnt(0)
	v_add_f32_e32 v53, v53, v72
	ds_bpermute_b32 v72, v46, v53
	s_waitcnt lgkmcnt(0)
	v_add_f32_e32 v53, v53, v72
	ds_bpermute_b32 v72, v47, v53
	s_waitcnt lgkmcnt(0)
	v_add_f32_e32 v53, v53, v72
	ds_bpermute_b32 v72, v48, v53
	s_waitcnt lgkmcnt(0)
	v_add_f32_e32 v53, v53, v72
	ds_bpermute_b32 v72, v49, v53
	s_waitcnt lgkmcnt(0)
	v_add_f32_e32 v53, v53, v72
	v_fmamk_f32 v53, v53, 0x3a800000, v149
	v_cmp_gt_f32_e32 vcc, s26, v53
	v_mul_f32_e32 v72, 0x4b800000, v53
	s_nop 0
	v_cndmask_b32_e32 v53, v53, v72, vcc
	v_rsq_f32_e32 v53, v53
	s_nop 0
	v_mul_f32_e32 v72, 0x45800000, v53
	v_cndmask_b32_e32 v72, v53, v72, vcc
	v_pk_mul_f32 v[54:55], v[72:73], v[54:55] op_sel_hi:[0,1]
	v_pk_mul_f32 v[56:57], v[72:73], v[56:57] op_sel_hi:[0,1]
	v_pk_fma_f32 v[54:55], v[54:55], v[28:29], v[2:3]
	v_pk_fma_f32 v[56:57], v[56:57], v[30:31], v[4:5]
	v_cvt_pk_bf16_f32 v54, v54, v55
	v_cvt_pk_bf16_f32 v55, v56, v57
	global_store_dwordx2 v[70:71], v[54:55], off offset:-1024
	v_pk_mul_f32 v[54:55], v[72:73], v[58:59] op_sel_hi:[0,1]
	v_pk_mul_f32 v[56:57], v[72:73], v[60:61] op_sel_hi:[0,1]
	v_pk_fma_f32 v[54:55], v[54:55], v[32:33], v[6:7]
	v_pk_fma_f32 v[56:57], v[56:57], v[34:35], v[8:9]
	v_cvt_pk_bf16_f32 v54, v54, v55
	v_cvt_pk_bf16_f32 v55, v56, v57
	global_store_dwordx2 v[70:71], v[54:55], off offset:-512
	v_pk_mul_f32 v[54:55], v[72:73], v[62:63] op_sel_hi:[0,1]
	v_pk_mul_f32 v[56:57], v[72:73], v[64:65] op_sel_hi:[0,1]
	v_pk_fma_f32 v[54:55], v[54:55], v[36:37], v[10:11]
	v_pk_fma_f32 v[56:57], v[56:57], v[38:39], v[12:13]
	v_cvt_pk_bf16_f32 v54, v54, v55
	v_cvt_pk_bf16_f32 v55, v56, v57
	global_store_dwordx2 v[70:71], v[54:55], off
	v_pk_mul_f32 v[54:55], v[72:73], v[66:67] op_sel_hi:[0,1]
	v_pk_mul_f32 v[56:57], v[72:73], v[68:69] op_sel_hi:[0,1]
	v_pk_fma_f32 v[54:55], v[54:55], v[40:41], v[14:15]
	v_pk_fma_f32 v[56:57], v[56:57], v[42:43], v[16:17]
	v_cvt_pk_bf16_f32 v54, v54, v55
	v_cvt_pk_bf16_f32 v55, v56, v57
	global_store_dwordx2 v[70:71], v[54:55], off offset:512
	s_add_u32 s6, s6, 0x800
	s_addc_u32 s7, s7, 0
	v_lshl_add_u64 v[70:71], v[26:27], 0, s[6:7]
	s_waitcnt vmcnt(20)
	v_mov_b32_e32 v80, v83
	v_mov_b32_e32 v81, v87
	v_mov_b32_e32 v78, v82
	v_mov_b32_e32 v79, v86
	v_pk_mul_f32 v[80:81], v[80:81], v[80:81]
	v_mov_b32_e32 v74, v84
	v_mov_b32_e32 v75, v88
	v_pk_fma_f32 v[78:79], v[78:79], v[78:79], v[80:81]
	v_mov_b32_e32 v76, v85
	v_mov_b32_e32 v77, v89
	v_pk_fma_f32 v[74:75], v[74:75], v[74:75], v[78:79]
	s_nop 0
	v_pk_fma_f32 v[72:73], v[76:77], v[76:77], v[74:75]
	s_nop 0
	v_add_f32_e32 v53, v72, v73
	v_mov_b32_e32 v80, v91
	v_mov_b32_e32 v81, v95
	v_mov_b32_e32 v78, v90
	v_mov_b32_e32 v79, v94
	v_pk_mul_f32 v[80:81], v[80:81], v[80:81]
	v_mov_b32_e32 v74, v92
	v_mov_b32_e32 v75, v96
	v_pk_fma_f32 v[78:79], v[78:79], v[78:79], v[80:81]
	v_mov_b32_e32 v76, v93
	v_mov_b32_e32 v77, v97
	v_pk_fma_f32 v[74:75], v[74:75], v[74:75], v[78:79]
	s_nop 0
	v_pk_fma_f32 v[74:75], v[76:77], v[76:77], v[74:75]
	s_nop 0
	v_add_f32_e32 v53, v53, v74
	v_add_f32_e32 v53, v53, v75
	ds_bpermute_b32 v72, v44, v53
	s_waitcnt lgkmcnt(0)
	v_add_f32_e32 v53, v53, v72
	ds_bpermute_b32 v72, v45, v53
	s_waitcnt lgkmcnt(0)
	v_add_f32_e32 v53, v53, v72
	ds_bpermute_b32 v72, v46, v53
	s_waitcnt lgkmcnt(0)
	v_add_f32_e32 v53, v53, v72
	ds_bpermute_b32 v72, v47, v53
	s_waitcnt lgkmcnt(0)
	v_add_f32_e32 v53, v53, v72
	ds_bpermute_b32 v72, v48, v53
	s_waitcnt lgkmcnt(0)
	v_add_f32_e32 v53, v53, v72
	ds_bpermute_b32 v72, v49, v53
	s_waitcnt lgkmcnt(0)
	v_add_f32_e32 v53, v53, v72
	v_fmamk_f32 v53, v53, 0x3a800000, v149
	v_cmp_gt_f32_e32 vcc, s26, v53
	v_mul_f32_e32 v72, 0x4b800000, v53
	s_nop 0
	v_cndmask_b32_e32 v53, v53, v72, vcc
	v_rsq_f32_e32 v53, v53
	s_nop 0
	v_mul_f32_e32 v72, 0x45800000, v53
	v_cndmask_b32_e32 v72, v53, v72, vcc
	v_pk_mul_f32 v[82:83], v[72:73], v[82:83] op_sel_hi:[0,1]
	v_pk_mul_f32 v[84:85], v[72:73], v[84:85] op_sel_hi:[0,1]
	v_pk_fma_f32 v[82:83], v[82:83], v[28:29], v[2:3]
	v_pk_fma_f32 v[84:85], v[84:85], v[30:31], v[4:5]
	v_cvt_pk_bf16_f32 v82, v82, v83
	v_cvt_pk_bf16_f32 v83, v84, v85
	global_store_dwordx2 v[70:71], v[82:83], off offset:-1024
	v_pk_mul_f32 v[82:83], v[72:73], v[86:87] op_sel_hi:[0,1]
	v_pk_mul_f32 v[84:85], v[72:73], v[88:89] op_sel_hi:[0,1]
	v_pk_fma_f32 v[82:83], v[82:83], v[32:33], v[6:7]
	v_pk_fma_f32 v[84:85], v[84:85], v[34:35], v[8:9]
	v_cvt_pk_bf16_f32 v82, v82, v83
	v_cvt_pk_bf16_f32 v83, v84, v85
	global_store_dwordx2 v[70:71], v[82:83], off offset:-512
	v_pk_mul_f32 v[82:83], v[72:73], v[90:91] op_sel_hi:[0,1]
	v_pk_mul_f32 v[84:85], v[72:73], v[92:93] op_sel_hi:[0,1]
	v_pk_fma_f32 v[82:83], v[82:83], v[36:37], v[10:11]
	v_pk_fma_f32 v[84:85], v[84:85], v[38:39], v[12:13]
	v_cvt_pk_bf16_f32 v82, v82, v83
	v_cvt_pk_bf16_f32 v83, v84, v85
	global_store_dwordx2 v[70:71], v[82:83], off
	v_pk_mul_f32 v[82:83], v[72:73], v[94:95] op_sel_hi:[0,1]
	v_pk_mul_f32 v[84:85], v[72:73], v[96:97] op_sel_hi:[0,1]
	v_pk_fma_f32 v[82:83], v[82:83], v[40:41], v[14:15]
	v_pk_fma_f32 v[84:85], v[84:85], v[42:43], v[16:17]
	v_cvt_pk_bf16_f32 v82, v82, v83
	v_cvt_pk_bf16_f32 v83, v84, v85
	global_store_dwordx2 v[70:71], v[82:83], off offset:512
	s_add_u32 s6, s6, 0x800
	s_addc_u32 s7, s7, 0
	v_lshl_add_u64 v[70:71], v[26:27], 0, s[6:7]
	s_waitcnt vmcnt(16)
	v_mov_b32_e32 v80, v99
	v_mov_b32_e32 v81, v103
	v_mov_b32_e32 v78, v98
	v_mov_b32_e32 v79, v102
	v_pk_mul_f32 v[80:81], v[80:81], v[80:81]
	v_mov_b32_e32 v74, v100
	v_mov_b32_e32 v75, v104
	v_pk_fma_f32 v[78:79], v[78:79], v[78:79], v[80:81]
	v_mov_b32_e32 v76, v101
	v_mov_b32_e32 v77, v105
	v_pk_fma_f32 v[74:75], v[74:75], v[74:75], v[78:79]
	s_nop 0
	v_pk_fma_f32 v[72:73], v[76:77], v[76:77], v[74:75]
	s_nop 0
	v_add_f32_e32 v53, v72, v73
	v_mov_b32_e32 v80, v107
	v_mov_b32_e32 v81, v111
	v_mov_b32_e32 v78, v106
	v_mov_b32_e32 v79, v110
	v_pk_mul_f32 v[80:81], v[80:81], v[80:81]
	v_mov_b32_e32 v74, v108
	v_mov_b32_e32 v75, v112
	v_pk_fma_f32 v[78:79], v[78:79], v[78:79], v[80:81]
	v_mov_b32_e32 v76, v109
	v_mov_b32_e32 v77, v113
	v_pk_fma_f32 v[74:75], v[74:75], v[74:75], v[78:79]
	s_nop 0
	v_pk_fma_f32 v[74:75], v[76:77], v[76:77], v[74:75]
	s_nop 0
	v_add_f32_e32 v53, v53, v74
	v_add_f32_e32 v53, v53, v75
	ds_bpermute_b32 v72, v44, v53
	s_waitcnt lgkmcnt(0)
	v_add_f32_e32 v53, v53, v72
	ds_bpermute_b32 v72, v45, v53
	s_waitcnt lgkmcnt(0)
	v_add_f32_e32 v53, v53, v72
	ds_bpermute_b32 v72, v46, v53
	s_waitcnt lgkmcnt(0)
	v_add_f32_e32 v53, v53, v72
	ds_bpermute_b32 v72, v47, v53
	s_waitcnt lgkmcnt(0)
	v_add_f32_e32 v53, v53, v72
	ds_bpermute_b32 v72, v48, v53
	s_waitcnt lgkmcnt(0)
	v_add_f32_e32 v53, v53, v72
	ds_bpermute_b32 v72, v49, v53
	s_waitcnt lgkmcnt(0)
	v_add_f32_e32 v53, v53, v72
	v_fmamk_f32 v53, v53, 0x3a800000, v149
	v_cmp_gt_f32_e32 vcc, s26, v53
	v_mul_f32_e32 v72, 0x4b800000, v53
	s_nop 0
	v_cndmask_b32_e32 v53, v53, v72, vcc
	v_rsq_f32_e32 v53, v53
	s_nop 0
	v_mul_f32_e32 v72, 0x45800000, v53
	v_cndmask_b32_e32 v72, v53, v72, vcc
	v_pk_mul_f32 v[98:99], v[72:73], v[98:99] op_sel_hi:[0,1]
	v_pk_mul_f32 v[100:101], v[72:73], v[100:101] op_sel_hi:[0,1]
	v_pk_fma_f32 v[98:99], v[98:99], v[28:29], v[2:3]
	v_pk_fma_f32 v[100:101], v[100:101], v[30:31], v[4:5]
	v_cvt_pk_bf16_f32 v98, v98, v99
	v_cvt_pk_bf16_f32 v99, v100, v101
	global_store_dwordx2 v[70:71], v[98:99], off offset:-1024
	v_pk_mul_f32 v[98:99], v[72:73], v[102:103] op_sel_hi:[0,1]
	v_pk_mul_f32 v[100:101], v[72:73], v[104:105] op_sel_hi:[0,1]
	v_pk_fma_f32 v[98:99], v[98:99], v[32:33], v[6:7]
	v_pk_fma_f32 v[100:101], v[100:101], v[34:35], v[8:9]
	v_cvt_pk_bf16_f32 v98, v98, v99
	v_cvt_pk_bf16_f32 v99, v100, v101
	global_store_dwordx2 v[70:71], v[98:99], off offset:-512
	v_pk_mul_f32 v[98:99], v[72:73], v[106:107] op_sel_hi:[0,1]
	v_pk_mul_f32 v[100:101], v[72:73], v[108:109] op_sel_hi:[0,1]
	v_pk_fma_f32 v[98:99], v[98:99], v[36:37], v[10:11]
	v_pk_fma_f32 v[100:101], v[100:101], v[38:39], v[12:13]
	v_cvt_pk_bf16_f32 v98, v98, v99
	v_cvt_pk_bf16_f32 v99, v100, v101
	global_store_dwordx2 v[70:71], v[98:99], off
	v_pk_mul_f32 v[98:99], v[72:73], v[110:111] op_sel_hi:[0,1]
	v_pk_mul_f32 v[100:101], v[72:73], v[112:113] op_sel_hi:[0,1]
	v_pk_fma_f32 v[98:99], v[98:99], v[40:41], v[14:15]
	v_pk_fma_f32 v[100:101], v[100:101], v[42:43], v[16:17]
	v_cvt_pk_bf16_f32 v98, v98, v99
	v_cvt_pk_bf16_f32 v99, v100, v101
	global_store_dwordx2 v[70:71], v[98:99], off offset:512
	s_add_u32 s6, s6, 0x800
	s_addc_u32 s7, s7, 0
	v_lshl_add_u64 v[70:71], v[26:27], 0, s[6:7]
	s_waitcnt vmcnt(12)
	v_mov_b32_e32 v80, v115
	v_mov_b32_e32 v81, v119
	v_mov_b32_e32 v78, v114
	v_mov_b32_e32 v79, v118
	v_pk_mul_f32 v[80:81], v[80:81], v[80:81]
	v_mov_b32_e32 v74, v116
	v_mov_b32_e32 v75, v120
	v_pk_fma_f32 v[78:79], v[78:79], v[78:79], v[80:81]
	v_mov_b32_e32 v76, v117
	v_mov_b32_e32 v77, v121
	v_pk_fma_f32 v[74:75], v[74:75], v[74:75], v[78:79]
	s_nop 0
	v_pk_fma_f32 v[72:73], v[76:77], v[76:77], v[74:75]
	s_nop 0
	v_add_f32_e32 v53, v72, v73
	v_mov_b32_e32 v80, v123
	v_mov_b32_e32 v81, v127
	v_mov_b32_e32 v78, v122
	v_mov_b32_e32 v79, v126
	v_pk_mul_f32 v[80:81], v[80:81], v[80:81]
	v_mov_b32_e32 v74, v124
	v_mov_b32_e32 v75, v128
	v_pk_fma_f32 v[78:79], v[78:79], v[78:79], v[80:81]
	v_mov_b32_e32 v76, v125
	v_mov_b32_e32 v77, v129
	v_pk_fma_f32 v[74:75], v[74:75], v[74:75], v[78:79]
	s_nop 0
	v_pk_fma_f32 v[74:75], v[76:77], v[76:77], v[74:75]
	s_nop 0
	v_add_f32_e32 v53, v53, v74
	v_add_f32_e32 v53, v53, v75
	ds_bpermute_b32 v72, v44, v53
	s_waitcnt lgkmcnt(0)
	v_add_f32_e32 v53, v53, v72
	ds_bpermute_b32 v72, v45, v53
	s_waitcnt lgkmcnt(0)
	v_add_f32_e32 v53, v53, v72
	ds_bpermute_b32 v72, v46, v53
	s_waitcnt lgkmcnt(0)
	v_add_f32_e32 v53, v53, v72
	ds_bpermute_b32 v72, v47, v53
	s_waitcnt lgkmcnt(0)
	v_add_f32_e32 v53, v53, v72
	ds_bpermute_b32 v72, v48, v53
	s_waitcnt lgkmcnt(0)
	v_add_f32_e32 v53, v53, v72
	ds_bpermute_b32 v72, v49, v53
	s_waitcnt lgkmcnt(0)
	v_add_f32_e32 v53, v53, v72
	v_fmamk_f32 v53, v53, 0x3a800000, v149
	v_cmp_gt_f32_e32 vcc, s26, v53
	v_mul_f32_e32 v72, 0x4b800000, v53
	s_nop 0
	v_cndmask_b32_e32 v53, v53, v72, vcc
	v_rsq_f32_e32 v53, v53
	s_nop 0
	v_mul_f32_e32 v72, 0x45800000, v53
	v_cndmask_b32_e32 v72, v53, v72, vcc
	v_pk_mul_f32 v[114:115], v[72:73], v[114:115] op_sel_hi:[0,1]
	v_pk_mul_f32 v[116:117], v[72:73], v[116:117] op_sel_hi:[0,1]
	v_pk_fma_f32 v[114:115], v[114:115], v[28:29], v[2:3]
	v_pk_fma_f32 v[116:117], v[116:117], v[30:31], v[4:5]
	v_cvt_pk_bf16_f32 v114, v114, v115
	v_cvt_pk_bf16_f32 v115, v116, v117
	global_store_dwordx2 v[70:71], v[114:115], off offset:-1024
	v_pk_mul_f32 v[114:115], v[72:73], v[118:119] op_sel_hi:[0,1]
	v_pk_mul_f32 v[116:117], v[72:73], v[120:121] op_sel_hi:[0,1]
	v_pk_fma_f32 v[114:115], v[114:115], v[32:33], v[6:7]
	v_pk_fma_f32 v[116:117], v[116:117], v[34:35], v[8:9]
	v_cvt_pk_bf16_f32 v114, v114, v115
	v_cvt_pk_bf16_f32 v115, v116, v117
	global_store_dwordx2 v[70:71], v[114:115], off offset:-512
	v_pk_mul_f32 v[114:115], v[72:73], v[122:123] op_sel_hi:[0,1]
	v_pk_mul_f32 v[116:117], v[72:73], v[124:125] op_sel_hi:[0,1]
	v_pk_fma_f32 v[114:115], v[114:115], v[36:37], v[10:11]
	v_pk_fma_f32 v[116:117], v[116:117], v[38:39], v[12:13]
	v_cvt_pk_bf16_f32 v114, v114, v115
	v_cvt_pk_bf16_f32 v115, v116, v117
	global_store_dwordx2 v[70:71], v[114:115], off
	v_pk_mul_f32 v[114:115], v[72:73], v[126:127] op_sel_hi:[0,1]
	v_pk_mul_f32 v[116:117], v[72:73], v[128:129] op_sel_hi:[0,1]
	v_pk_fma_f32 v[114:115], v[114:115], v[40:41], v[14:15]
	v_pk_fma_f32 v[116:117], v[116:117], v[42:43], v[16:17]
	v_cvt_pk_bf16_f32 v114, v114, v115
	v_cvt_pk_bf16_f32 v115, v116, v117
	global_store_dwordx2 v[70:71], v[114:115], off offset:512
	s_add_u32 s6, s6, 0x800
	s_addc_u32 s7, s7, 0
	s_add_i32 s4, s4, s3
	s_cmpk_gt_i32 s4, 0xff
	s_cbranch_scc0 .LBB0_530
